# compressed-branch PV: V_cmp tile staged once per unit in LDS (XOR-swizzled, 16 KB of static LDS added) instead of 32 dwordx2 global loads per lane; ds_read_b128 fragments
# speedup vs baseline: 1.0230x; 1.0166x over previous
.LBB0_48:
	v_readlane_b32 s0, v252, 57
	s_bfe_u32 s4, s0, 0x70001
	s_bfe_u32 s0, s0, 0x20001
	v_lshl_add_u32 v2, s0, 9, v172
	v_readlane_b32 s2, v252, 62
	v_ashrrev_i32_e32 v3, 31, v2
	v_readlane_b32 s3, v252, 63
	s_waitcnt vmcnt(2)
	v_and_b32_e32 v47, 0xffff0000, v103
	v_writelane_b32 v253, s0, 0
	v_lshl_add_u64 v[2:3], v[2:3], 2, s[2:3]
	global_load_dword v1, v[2:3], off
	v_readlane_b32 s100, v252, 57
	s_bfe_u32 s100, s100, 0x70001
	s_lshl_b32 s100, s100, 14
	s_add_u32 s100, s100, 0x5000000
	v_readlane_b32 s101, v252, 62
	s_add_u32 s100, s100, s101
	v_readlane_b32 s101, v252, 63
	s_addc_u32 s101, s101, 0
	v_lshlrev_b32_e32 v6, 5, v172
	global_load_dwordx4 v[8:11], v6, s[100:101]
	global_load_dwordx4 v[12:15], v6, s[100:101] offset:16
	v_add_u32_e32 v92, 0x200000, v6
	global_load_dwordx4 v[84:87], v92, s[100:101]
	global_load_dwordx4 v[88:91], v92, s[100:101] offset:16
	v_readlane_b32 s0, v252, 58
	v_readlane_b32 s1, v252, 59
	v_and_b32_e32 v2, 64, v209
	s_load_dwordx2 s[0:1], s[0:1], 0xf0
	v_add_u32_e32 v195, 64, v2
	v_lshlrev_b32_e32 v46, 16, v103
	v_mul_f32_e32 v50, v47, v47
	v_pk_fma_f32 v[58:59], v[46:47], v[46:47], v[50:51] op_sel_hi:[1,1,0]
	v_and_b32_e32 v51, 0xffff0000, v102
	v_lshlrev_b32_e32 v50, 16, v102
	v_mul_f32_e32 v54, v51, v51
	v_pk_fma_f32 v[60:61], v[50:51], v[50:51], v[54:55] op_sel_hi:[1,1,0]
	v_and_b32_e32 v55, 0xffff0000, v101
	v_and_b32_e32 v57, 0xffff0000, v100
	v_lshlrev_b32_e32 v54, 16, v101
	v_lshlrev_b32_e32 v56, 16, v100
	v_mov_b32_e32 v64, v55
	v_mov_b32_e32 v65, v57
	v_mov_b32_e32 v62, v54
	v_mov_b32_e32 v63, v56
	v_pk_mul_f32 v[64:65], v[64:65], v[64:65]
	v_and_b32_e32 v77, 0xffff0000, v106
	v_pk_fma_f32 v[66:67], v[62:63], v[62:63], v[64:65]
	v_and_b32_e32 v63, 0xffff0000, v99
	v_and_b32_e32 v65, 0xffff0000, v98
	v_lshlrev_b32_e32 v62, 16, v99
	v_lshlrev_b32_e32 v64, 16, v98
	v_mov_b32_e32 v70, v65
	v_mov_b32_e32 v71, v63
	v_mov_b32_e32 v68, v64
	v_mov_b32_e32 v69, v62
	v_pk_mul_f32 v[70:71], v[70:71], v[70:71]
	v_lshlrev_b32_e32 v76, 16, v106
	v_pk_fma_f32 v[68:69], v[68:69], v[68:69], v[70:71]
	v_and_b32_e32 v71, 0xffff0000, v108
	v_pk_add_f32 v[68:69], v[68:69], v[68:69] op_sel:[0,1] op_sel_hi:[1,0]
	v_lshlrev_b32_e32 v70, 16, v108
	v_pk_add_f32 v[68:69], v[66:67], v[68:69] op_sel:[1,0] op_sel_hi:[0,1]
	v_pk_add_f32 v[66:67], v[66:67], v[68:69]
	v_and_b32_e32 v69, 0xffff0000, v109
	v_lshlrev_b32_e32 v68, 16, v109
	v_mov_b32_e32 v74, v69
	v_mov_b32_e32 v75, v71
	v_mov_b32_e32 v72, v68
	v_mov_b32_e32 v73, v70
	v_pk_mul_f32 v[74:75], v[74:75], v[74:75]
	v_mov_b32_e32 v80, v77
	v_pk_fma_f32 v[72:73], v[72:73], v[72:73], v[74:75]
	v_and_b32_e32 v75, 0xffff0000, v107
	v_lshlrev_b32_e32 v74, 16, v107
	v_mov_b32_e32 v81, v75
	v_mov_b32_e32 v78, v76
	v_mov_b32_e32 v79, v74
	v_pk_mul_f32 v[80:81], v[80:81], v[80:81]
	s_waitcnt vmcnt(6)
	v_and_b32_e32 v37, 0xffff0000, v112
	v_pk_fma_f32 v[78:79], v[78:79], v[78:79], v[80:81]
	v_and_b32_e32 v43, 0xffff0000, v105
	v_pk_add_f32 v[78:79], v[78:79], v[78:79] op_sel:[0,1] op_sel_hi:[1,0]
	v_lshlrev_b32_e32 v36, 16, v112
	v_lshlrev_b32_e32 v38, 16, v111
	v_and_b32_e32 v39, 0xffff0000, v111
	v_and_b32_e32 v41, 0xffff0000, v110
	v_lshlrev_b32_e32 v42, 16, v105
	v_and_b32_e32 v45, 0xffff0000, v104
	v_pk_add_f32 v[78:79], v[72:73], v[78:79] op_sel:[1,0] op_sel_hi:[0,1]
	v_mov_b32_e32 v80, v43
	v_mov_b32_e32 v81, v37
	v_pk_mul_f32 v[52:53], v[38:39], v[38:39]
	v_lshlrev_b32_e32 v40, 16, v110
	v_lshlrev_b32_e32 v44, 16, v104
	v_pk_add_f32 v[72:73], v[72:73], v[78:79]
	v_mov_b32_e32 v78, v42
	v_mov_b32_e32 v79, v36
	v_pk_mul_f32 v[80:81], v[80:81], v[80:81]
	v_mov_b32_e32 v82, v45
	v_mov_b32_e32 v83, v41
	v_lshlrev_b32_e32 v34, 16, v113
	v_and_b32_e32 v35, 0xffff0000, v113
	v_pk_fma_f32 v[78:79], v[78:79], v[78:79], v[80:81]
	s_waitcnt vmcnt(0)
	v_mul_f32_e32 v1, 0x3fb8aa3b, v1
	ds_write_b32 v169, v1
	v_lshrrev_b32_e32 v2, 7, v172
	v_lshlrev_b32_e32 v3, 2, v172
	v_lshl_add_u32 v3, v2, 9, v3
	v_bfe_u32 v4, v172, 6, 1
	v_readlane_b32 s100, v1, 63
	v_add_u32_e32 v5, 0x22200, v3
	ds_write_b32 v5, v1
	v_lshl_add_u32 v3, v4, 9, v3
	v_cmp_ne_u32_e32 vcc, 0, v4
	v_mov_b32_e32 v5, s100
	v_add_u32_e32 v3, 0x22100, v3
	v_cndmask_b32_e32 v5, v210, v5, vcc
	ds_write_b32 v3, v5
	v_add_u32_e32 v7, v223, v224
	ds_write_b128 v7, v[8:11] offset:36864
	ds_write_b128 v7, v[12:15] offset:36880
	v_lshrrev_b32_e32 v93, 3, v172
	v_xor_b32_e32 v92, v93, v172
	v_and_b32_e32 v92, 7, v92
	v_lshlrev_b32_e32 v93, 8, v93
	v_lshl_add_u32 v93, v92, 5, v93
	v_add_u32_e32 v93, 0x24000, v93
	ds_write2_b64 v93, v[84:85], v[86:87] offset1:2
	ds_write2_b64 v93, v[88:89], v[90:91] offset0:1 offset1:3
	v_xor_b32_e32 v1, 32, v209
	v_cmp_lt_i32_e32 vcc, v1, v195
	v_mov_b32_e32 v80, v44
	v_mov_b32_e32 v81, v40
	v_cndmask_b32_e32 v1, v209, v1, vcc
	v_lshlrev_b32_e32 v163, 2, v1
	v_lshlrev_b32_e32 v1, 2, v174
	s_waitcnt lgkmcnt(0)
	global_load_dwordx4 v[26:29], v1, s[0:1] offset:16
	global_load_dwordx4 v[30:33], v1, s[0:1]
	global_load_dwordx4 v[18:21], v1, s[0:1] offset:80
	global_load_dwordx4 v[22:25], v1, s[0:1] offset:64
	global_load_dwordx4 v[10:13], v1, s[0:1] offset:144
	global_load_dwordx4 v[14:17], v1, s[0:1] offset:128
	global_load_dwordx4 v[2:5], v1, s[0:1] offset:208
	global_load_dwordx4 v[6:9], v1, s[0:1] offset:192
	v_pk_mul_f32 v[82:83], v[82:83], v[82:83]
	v_mov_b32_e32 v61, v52
	v_mov_b32_e32 v59, v53
	v_pk_mul_f32 v[48:49], v[34:35], v[34:35]
	v_pk_fma_f32 v[80:81], v[80:81], v[80:81], v[82:83]
	v_pk_add_f32 v[52:53], v[60:61], v[58:59]
	v_mov_b32_e32 v73, v48
	v_pk_add_f32 v[52:53], v[80:81], v[52:53]
	v_mov_b32_e32 v67, v49
	v_pk_add_f32 v[52:53], v[78:79], v[52:53]
	v_pk_add_f32 v[48:49], v[72:73], v[66:67]
	s_mov_b32 s0, 0x800000
	v_pk_add_f32 v[48:49], v[48:49], v[52:53]
	s_lshl_b32 s5, s50, 6
	v_add_f32_e32 v1, v48, v49
	ds_bpermute_b32 v48, v163, v1
	v_lshlrev_b32_e32 v96, 1, v174
	v_mov_b32_e32 v187, v97
	s_waitcnt lgkmcnt(0)
	s_barrier
	v_add_f32_e32 v1, v1, v48
	v_fmamk_f32 v1, v1, 0x3c800000, v207
	v_cmp_gt_f32_e32 vcc, s0, v1
	v_mul_f32_e32 v48, 0x4b800000, v1
	s_lshl_b32 s0, s4, 14
	v_cndmask_b32_e32 v1, v1, v48, vcc
	v_rsq_f32_e32 v1, v1
	s_add_u32 s0, s2, s0
	s_addc_u32 s1, s3, 0
	v_mul_f32_e32 v48, 0x45800000, v1
	v_cndmask_b32_e32 v1, v1, v48, vcc
	v_mul_f32_e32 v48, 0x3e38aa3b, v1
	v_pk_mul_f32 v[52:53], v[48:49], v[76:77] op_sel_hi:[0,1]
	v_mul_f32_e32 v0, 0xbfb8aa3b, v164
	v_writelane_b32 v253, s4, 1
	s_waitcnt vmcnt(6)
	v_pk_mul_f32 v[30:31], v[30:31], v[52:53]
	s_nop 0
	v_cvt_pk_bf16_f32 v114, v30, v31
	v_pk_mul_f32 v[30:31], v[48:49], v[74:75] op_sel_hi:[0,1]
	v_pk_mul_f32 v[30:31], v[32:33], v[30:31]
	s_nop 0
	v_cvt_pk_bf16_f32 v115, v30, v31
	v_pk_mul_f32 v[30:31], v[48:49], v[70:71] op_sel_hi:[0,1]
	v_pk_mul_f32 v[26:27], v[26:27], v[30:31]
	s_nop 0
	v_cvt_pk_bf16_f32 v116, v26, v27
	v_pk_mul_f32 v[26:27], v[48:49], v[68:69] op_sel_hi:[0,1]
	v_pk_mul_f32 v[26:27], v[28:29], v[26:27]
	s_nop 0
	v_cvt_pk_bf16_f32 v117, v26, v27
	v_pk_mul_f32 v[26:27], v[48:49], v[64:65] op_sel_hi:[0,1]
	s_waitcnt vmcnt(4)
	v_pk_mul_f32 v[22:23], v[22:23], v[26:27]
	s_nop 0
	v_cvt_pk_bf16_f32 v118, v22, v23
	v_pk_mul_f32 v[22:23], v[48:49], v[62:63] op_sel_hi:[0,1]
	v_pk_mul_f32 v[22:23], v[24:25], v[22:23]
	s_nop 0
	v_cvt_pk_bf16_f32 v119, v22, v23
	v_pk_mul_f32 v[22:23], v[48:49], v[56:57] op_sel_hi:[0,1]
	v_pk_mul_f32 v[18:19], v[18:19], v[22:23]
	s_nop 0
	v_cvt_pk_bf16_f32 v120, v18, v19
	v_pk_mul_f32 v[18:19], v[48:49], v[54:55] op_sel_hi:[0,1]
	v_pk_mul_f32 v[18:19], v[20:21], v[18:19]
	s_nop 0
	v_cvt_pk_bf16_f32 v121, v18, v19
	v_pk_mul_f32 v[18:19], v[48:49], v[50:51] op_sel_hi:[0,1]
	s_waitcnt vmcnt(2)
	v_pk_mul_f32 v[14:15], v[14:15], v[18:19]
	s_nop 0
	v_cvt_pk_bf16_f32 v122, v14, v15
	v_pk_mul_f32 v[14:15], v[48:49], v[46:47] op_sel_hi:[0,1]
	v_pk_mul_f32 v[14:15], v[16:17], v[14:15]
	s_nop 0
	v_cvt_pk_bf16_f32 v123, v14, v15
	v_pk_mul_f32 v[14:15], v[48:49], v[44:45] op_sel_hi:[0,1]
	v_pk_mul_f32 v[10:11], v[10:11], v[14:15]
	s_nop 0
	v_cvt_pk_bf16_f32 v124, v10, v11
	v_pk_mul_f32 v[10:11], v[48:49], v[42:43] op_sel_hi:[0,1]
	v_pk_mul_f32 v[10:11], v[12:13], v[10:11]
	s_nop 0
	v_cvt_pk_bf16_f32 v125, v10, v11
	v_pk_mul_f32 v[10:11], v[48:49], v[40:41] op_sel_hi:[0,1]
	s_waitcnt vmcnt(0)
	v_pk_mul_f32 v[6:7], v[6:7], v[10:11]
	s_nop 0
	v_cvt_pk_bf16_f32 v126, v6, v7
	v_pk_mul_f32 v[6:7], v[48:49], v[38:39] op_sel_hi:[0,1]
	v_pk_mul_f32 v[6:7], v[8:9], v[6:7]
	s_nop 0
	v_cvt_pk_bf16_f32 v127, v6, v7
	v_pk_mul_f32 v[6:7], v[48:49], v[36:37] op_sel_hi:[0,1]
	v_pk_mul_f32 v[2:3], v[2:3], v[6:7]
	s_nop 0
	v_cvt_pk_bf16_f32 v128, v2, v3
	v_pk_mul_f32 v[2:3], v[48:49], v[34:35] op_sel_hi:[0,1]
	v_pk_mul_f32 v[2:3], v[4:5], v[2:3]
	s_nop 0
	v_cvt_pk_bf16_f32 v129, v2, v3
	v_add_u32_e32 v131, v227, v229
	ds_read_b128 v[64:67], v131 offset:41472
	ds_read_b128 v[16:19], v131 offset:36864
	ds_read_b128 v[68:71], v131 offset:41504
	ds_read_b128 v[20:23], v131 offset:36896
	ds_read_b128 v[72:75], v131 offset:41536
	ds_read_b128 v[24:27], v131 offset:36928
	ds_read_b128 v[76:79], v131 offset:41568
	ds_read_b128 v[28:31], v131 offset:36960
	v_mov_b32_e32 v1, v0
	v_mov_b32_e32 v2, v0
	v_mov_b32_e32 v3, v0
	v_mov_b32_e32 v4, v0
	v_mov_b32_e32 v5, v0
	v_mov_b32_e32 v6, v0
	v_mov_b32_e32 v7, v0
	v_mov_b32_e32 v8, v0
	v_mov_b32_e32 v9, v0
	v_mov_b32_e32 v10, v0
	v_mov_b32_e32 v11, v0
	v_mov_b32_e32 v12, v0
	v_mov_b32_e32 v13, v0
	v_mov_b32_e32 v14, v0
	v_mov_b32_e32 v15, v0
	s_waitcnt lgkmcnt(7)
	v_mfma_f32_32x32x16_bf16 v[32:47], v[64:67], v[114:117], v[0:15]
	s_waitcnt lgkmcnt(6)
	v_mfma_f32_32x32x16_bf16 v[48:63], v[16:19], v[114:117], v[0:15]
	s_waitcnt lgkmcnt(5)
	v_mfma_f32_32x32x16_bf16 v[32:47], v[68:71], v[118:121], v[32:47]
	s_waitcnt lgkmcnt(4)
	v_mfma_f32_32x32x16_bf16 v[48:63], v[20:23], v[118:121], v[48:63]
	s_waitcnt lgkmcnt(3)
	v_mfma_f32_32x32x16_bf16 v[32:47], v[72:75], v[122:125], v[32:47]
	s_waitcnt lgkmcnt(2)
	v_mfma_f32_32x32x16_bf16 v[48:63], v[24:27], v[122:125], v[48:63]
	s_waitcnt lgkmcnt(1)
	v_mfma_f32_32x32x16_bf16 v[32:47], v[76:79], v[126:129], v[32:47]
	s_waitcnt lgkmcnt(0)
	v_mfma_f32_32x32x16_bf16 v[48:63], v[28:31], v[126:129], v[48:63]
	ds_read_b128 v[64:67], v131 offset:46080
	ds_read_b128 v[80:83], v131 offset:50688
	ds_read_b128 v[68:71], v131 offset:46112
	ds_read_b128 v[84:87], v131 offset:50720
	ds_read_b128 v[72:75], v131 offset:46144
	ds_read_b128 v[88:91], v131 offset:50752
	ds_read_b128 v[76:79], v131 offset:46176
	ds_read_b128 v[92:95], v131 offset:50784
	s_waitcnt lgkmcnt(7)
	v_mfma_f32_32x32x16_bf16 v[16:31], v[64:67], v[114:117], v[0:15]
	v_or_b32_e32 v164, s5, v167
	v_sub_u32_e32 v66, v164, v175
	v_writelane_b32 v253, s5, 2
	s_waitcnt lgkmcnt(6)
	v_mfma_f32_32x32x16_bf16 v[0:15], v[80:83], v[114:117], v[0:15]
	s_waitcnt lgkmcnt(5)
	v_mfma_f32_32x32x16_bf16 v[16:31], v[68:71], v[118:121], v[16:31]
	s_waitcnt lgkmcnt(4)
	v_mfma_f32_32x32x16_bf16 v[0:15], v[84:87], v[118:121], v[0:15]
	s_waitcnt lgkmcnt(3)
	v_mfma_f32_32x32x16_bf16 v[16:31], v[72:75], v[122:125], v[16:31]
	s_waitcnt lgkmcnt(2)
	v_mfma_f32_32x32x16_bf16 v[0:15], v[88:91], v[122:125], v[0:15]
	s_waitcnt lgkmcnt(1)
	v_mfma_f32_32x32x16_bf16 v[16:31], v[76:79], v[126:129], v[16:31]
	s_waitcnt lgkmcnt(0)
	v_mfma_f32_32x32x16_bf16 v[0:15], v[92:95], v[126:129], v[0:15]
	v_add_u32_e32 v131, 0xffffffe1, v66
	v_min_u32_e32 v132, 0x7f, v131
	v_lshl_add_u32 v132, v132, 2, s33
	ds_read_b32 v132, v132
	v_ashrrev_i32_e32 v131, 31, v131
	v_add_u32_e32 v133, 0xffffffd1, v66
	v_min_u32_e32 v134, 0x7f, v133
	v_lshl_add_u32 v134, v134, 2, s33
	ds_read_b32 v134, v134
	v_ashrrev_i32_e32 v133, 31, v133
	v_add_u32_e32 v135, 0xffffffc1, v66
	v_min_u32_e32 v136, 0x7f, v135
	v_lshl_add_u32 v136, v136, 2, s33
	ds_read_b32 v136, v136
	v_ashrrev_i32_e32 v135, 31, v135
	v_add_u32_e32 v137, 0xffffffb1, v66
	v_min_u32_e32 v138, 0x7f, v137
	v_lshl_add_u32 v138, v138, 2, s33
	ds_read_b32 v138, v138
	v_ashrrev_i32_e32 v137, 31, v137
	v_add_u32_e32 v139, 0xffffff61, v66
	v_min_u32_e32 v140, 0x7f, v139
	v_lshl_add_u32 v140, v140, 2, s33
	ds_read_b32 v140, v140
	v_ashrrev_i32_e32 v139, 31, v139
	v_add_u32_e32 v141, 0xffffff51, v66
	v_min_u32_e32 v142, 0x7f, v141
	v_lshl_add_u32 v142, v142, 2, s33
	ds_read_b32 v142, v142
	v_ashrrev_i32_e32 v141, 31, v141
	v_add_u32_e32 v143, 0xffffff41, v66
	v_min_u32_e32 v144, 0x7f, v143
	v_lshl_add_u32 v144, v144, 2, s33
	ds_read_b32 v144, v144
	v_ashrrev_i32_e32 v143, 31, v143
	v_add_u32_e32 v145, 0xffffff31, v66
	v_min_u32_e32 v146, 0x7f, v145
	v_lshl_add_u32 v146, v146, 2, s33
	ds_read_b32 v146, v146
	v_ashrrev_i32_e32 v145, 31, v145
	v_add_u32_e32 v147, 0xfffffee1, v66
	v_min_u32_e32 v148, 0x7f, v147
	v_lshl_add_u32 v148, v148, 2, s33
	ds_read_b32 v148, v148
	v_ashrrev_i32_e32 v147, 31, v147
	v_add_u32_e32 v149, 0xfffffed1, v66
	v_min_u32_e32 v150, 0x7f, v149
	v_lshl_add_u32 v150, v150, 2, s33
	ds_read_b32 v150, v150
	v_ashrrev_i32_e32 v149, 31, v149
	v_add_u32_e32 v151, 0xfffffec1, v66
	v_min_u32_e32 v152, 0x7f, v151
	v_lshl_add_u32 v152, v152, 2, s33
	ds_read_b32 v152, v152
	v_ashrrev_i32_e32 v151, 31, v151
	v_add_u32_e32 v153, 0xfffffeb1, v66
	v_min_u32_e32 v154, 0x7f, v153
	v_lshl_add_u32 v154, v154, 2, s33
	ds_read_b32 v154, v154
	v_ashrrev_i32_e32 v153, 31, v153
	v_add_u32_e32 v155, 0xfffffe61, v66
	v_min_u32_e32 v156, 0x7f, v155
	v_lshl_add_u32 v156, v156, 2, s33
	ds_read_b32 v156, v156
	v_ashrrev_i32_e32 v155, 31, v155
	v_add_u32_e32 v157, 0xfffffe51, v66
	v_min_u32_e32 v158, 0x7f, v157
	v_lshl_add_u32 v158, v158, 2, s33
	ds_read_b32 v158, v158
	v_ashrrev_i32_e32 v157, 31, v157
	v_add_u32_e32 v159, 0xfffffe41, v66
	v_min_u32_e32 v160, 0x7f, v159
	v_lshl_add_u32 v160, v160, 2, s33
	ds_read_b32 v160, v160
	v_ashrrev_i32_e32 v159, 31, v159
	s_waitcnt lgkmcnt(14)
	v_add_f32_e32 v65, v48, v132
	v_exp_f32_e32 v65, v65
	s_nop 0
	v_bfi_b32 v65, v131, 0, v65
	v_add_u32_e32 v131, 0xfffffe31, v66
	v_min_u32_e32 v132, 0x7f, v131
	v_lshl_add_u32 v132, v132, 2, s33
	ds_read_b32 v132, v132
	v_ashrrev_i32_e32 v131, 31, v131
	s_waitcnt lgkmcnt(14)
	v_add_f32_e32 v64, v49, v134
	v_exp_f32_e32 v64, v64
	v_add_f32_e32 v161, 0, v65
	v_bfi_b32 v64, v133, 0, v64
	v_add_u32_e32 v133, 0xfffffde1, v66
	v_min_u32_e32 v134, 0x7f, v133
	v_lshl_add_u32 v134, v134, 2, s33
	ds_read_b32 v134, v134
	v_ashrrev_i32_e32 v133, 31, v133
	s_waitcnt lgkmcnt(14)
	v_add_f32_e32 v49, v50, v136
	v_exp_f32_e32 v49, v49
	v_add_f32_e32 v161, v161, v64
	v_bfi_b32 v49, v135, 0, v49
	v_add_u32_e32 v135, 0xfffffdd1, v66
	v_min_u32_e32 v136, 0x7f, v135
	v_lshl_add_u32 v136, v136, 2, s33
	ds_read_b32 v136, v136
	v_ashrrev_i32_e32 v135, 31, v135
	s_waitcnt lgkmcnt(14)
	v_add_f32_e32 v48, v51, v138
	v_exp_f32_e32 v48, v48
	v_add_f32_e32 v161, v161, v49
	v_bfi_b32 v48, v137, 0, v48
	v_add_u32_e32 v137, 0xfffffdc1, v66
	v_min_u32_e32 v138, 0x7f, v137
	v_lshl_add_u32 v138, v138, 2, s33
	ds_read_b32 v138, v138
	v_ashrrev_i32_e32 v137, 31, v137
	s_waitcnt lgkmcnt(14)
	v_add_f32_e32 v51, v52, v140
	v_exp_f32_e32 v51, v51
	v_add_f32_e32 v161, v161, v48
	v_bfi_b32 v51, v139, 0, v51
	v_add_u32_e32 v139, 0xfffffdb1, v66
	v_min_u32_e32 v140, 0x7f, v139
	v_lshl_add_u32 v140, v140, 2, s33
	ds_read_b32 v140, v140
	v_ashrrev_i32_e32 v139, 31, v139
	s_waitcnt lgkmcnt(14)
	v_add_f32_e32 v50, v53, v142
	v_exp_f32_e32 v50, v50
	v_add_f32_e32 v161, v161, v51
	v_bfi_b32 v50, v141, 0, v50
	v_add_u32_e32 v141, 0xfffffd61, v66
	v_min_u32_e32 v142, 0x7f, v141
	v_lshl_add_u32 v142, v142, 2, s33
	ds_read_b32 v142, v142
	v_ashrrev_i32_e32 v141, 31, v141
	s_waitcnt lgkmcnt(14)
	v_add_f32_e32 v53, v54, v144
	v_exp_f32_e32 v53, v53
	v_add_f32_e32 v161, v161, v50
	v_bfi_b32 v53, v143, 0, v53
	v_add_u32_e32 v143, 0xfffffd51, v66
	v_min_u32_e32 v144, 0x7f, v143
	v_lshl_add_u32 v144, v144, 2, s33
	ds_read_b32 v144, v144
	v_ashrrev_i32_e32 v143, 31, v143
	s_waitcnt lgkmcnt(14)
	v_add_f32_e32 v52, v55, v146
	v_exp_f32_e32 v52, v52
	v_add_f32_e32 v161, v161, v53
	v_bfi_b32 v52, v145, 0, v52
	v_add_u32_e32 v145, 0xfffffd41, v66
	v_min_u32_e32 v146, 0x7f, v145
	v_lshl_add_u32 v146, v146, 2, s33
	ds_read_b32 v146, v146
	v_ashrrev_i32_e32 v145, 31, v145
	s_waitcnt lgkmcnt(14)
	v_add_f32_e32 v55, v56, v148
	v_exp_f32_e32 v55, v55
	v_add_f32_e32 v161, v161, v52
	v_bfi_b32 v55, v147, 0, v55
	v_add_u32_e32 v147, 0xfffffd31, v66
	v_min_u32_e32 v148, 0x7f, v147
	v_lshl_add_u32 v148, v148, 2, s33
	ds_read_b32 v148, v148
	v_ashrrev_i32_e32 v147, 31, v147
	s_waitcnt lgkmcnt(14)
	v_add_f32_e32 v54, v57, v150
	v_exp_f32_e32 v54, v54
	v_add_f32_e32 v161, v161, v55
	v_bfi_b32 v54, v149, 0, v54
	v_add_u32_e32 v149, 0xfffffce1, v66
	v_min_u32_e32 v150, 0x7f, v149
	v_lshl_add_u32 v150, v150, 2, s33
	ds_read_b32 v150, v150
	v_ashrrev_i32_e32 v149, 31, v149
	s_waitcnt lgkmcnt(14)
	v_add_f32_e32 v57, v58, v152
	v_exp_f32_e32 v57, v57
	v_add_f32_e32 v161, v161, v54
	v_bfi_b32 v57, v151, 0, v57
	v_add_u32_e32 v151, 0xfffffcd1, v66
	v_min_u32_e32 v152, 0x7f, v151
	v_lshl_add_u32 v152, v152, 2, s33
	ds_read_b32 v152, v152
	v_ashrrev_i32_e32 v151, 31, v151
	s_waitcnt lgkmcnt(14)
	v_add_f32_e32 v56, v59, v154
	v_exp_f32_e32 v56, v56
	v_add_f32_e32 v161, v161, v57
	v_bfi_b32 v56, v153, 0, v56
	v_add_u32_e32 v153, 0xfffffcc1, v66
	v_min_u32_e32 v154, 0x7f, v153
	v_lshl_add_u32 v154, v154, 2, s33
	ds_read_b32 v154, v154
	v_ashrrev_i32_e32 v153, 31, v153
	s_waitcnt lgkmcnt(14)
	v_add_f32_e32 v59, v60, v156
	v_exp_f32_e32 v59, v59
	v_add_f32_e32 v161, v161, v56
	v_bfi_b32 v59, v155, 0, v59
	v_add_u32_e32 v155, 0xfffffcb1, v66
	v_min_u32_e32 v156, 0x7f, v155
	v_lshl_add_u32 v156, v156, 2, s33
	ds_read_b32 v156, v156
	v_ashrrev_i32_e32 v155, 31, v155
	s_waitcnt lgkmcnt(14)
	v_add_f32_e32 v58, v61, v158
	v_exp_f32_e32 v58, v58
	v_add_f32_e32 v161, v161, v59
	v_bfi_b32 v58, v157, 0, v58
	v_add_u32_e32 v157, 0xfffffc61, v66
	v_min_u32_e32 v158, 0x7f, v157
	v_lshl_add_u32 v158, v158, 2, s33
	ds_read_b32 v158, v158
	v_ashrrev_i32_e32 v157, 31, v157
	s_waitcnt lgkmcnt(14)
	v_add_f32_e32 v61, v62, v160
	v_exp_f32_e32 v61, v61
	v_add_f32_e32 v161, v161, v58
	v_bfi_b32 v61, v159, 0, v61
	v_add_u32_e32 v159, 0xfffffc51, v66
	v_min_u32_e32 v160, 0x7f, v159
	v_lshl_add_u32 v160, v160, 2, s33
	ds_read_b32 v160, v160
	v_ashrrev_i32_e32 v159, 31, v159
	s_waitcnt lgkmcnt(14)
	v_add_f32_e32 v60, v63, v132
	v_exp_f32_e32 v60, v60
	v_add_f32_e32 v161, v161, v61
	v_bfi_b32 v60, v131, 0, v60
	v_add_u32_e32 v131, 0xfffffc41, v66
	v_min_u32_e32 v132, 0x7f, v131
	v_lshl_add_u32 v132, v132, 2, s33
	ds_read_b32 v132, v132
	v_ashrrev_i32_e32 v131, 31, v131
	s_waitcnt lgkmcnt(14)
	v_add_f32_e32 v63, v32, v134
	v_exp_f32_e32 v63, v63
	v_add_f32_e32 v161, v161, v60
	v_bfi_b32 v63, v133, 0, v63
	v_add_u32_e32 v133, 0xfffffc31, v66
	v_min_u32_e32 v134, 0x7f, v133
	v_lshl_add_u32 v134, v134, 2, s33
	ds_read_b32 v134, v134
	v_ashrrev_i32_e32 v133, 31, v133
	s_waitcnt lgkmcnt(14)
	v_add_f32_e32 v62, v33, v136
	v_exp_f32_e32 v62, v62
	v_add_f32_e32 v161, v161, v63
	v_bfi_b32 v62, v135, 0, v62
	v_add_u32_e32 v135, 0xfffffbe1, v66
	v_min_u32_e32 v136, 0x7f, v135
	v_lshl_add_u32 v136, v136, 2, s33
	ds_read_b32 v136, v136
	v_ashrrev_i32_e32 v135, 31, v135
	s_waitcnt lgkmcnt(14)
	v_add_f32_e32 v33, v34, v138
	v_exp_f32_e32 v33, v33
	v_add_f32_e32 v161, v161, v62
	v_bfi_b32 v33, v137, 0, v33
	v_add_u32_e32 v137, 0xfffffbd1, v66
	v_min_u32_e32 v138, 0x7f, v137
	v_lshl_add_u32 v138, v138, 2, s33
	ds_read_b32 v138, v138
	v_ashrrev_i32_e32 v137, 31, v137
	s_waitcnt lgkmcnt(14)
	v_add_f32_e32 v32, v35, v140
	v_exp_f32_e32 v32, v32
	v_add_f32_e32 v161, v161, v33
	v_bfi_b32 v32, v139, 0, v32
	v_add_u32_e32 v139, 0xfffffbc1, v66
	v_min_u32_e32 v140, 0x7f, v139
	v_lshl_add_u32 v140, v140, 2, s33
	ds_read_b32 v140, v140
	v_ashrrev_i32_e32 v139, 31, v139
	s_waitcnt lgkmcnt(14)
	v_add_f32_e32 v35, v36, v142
	v_exp_f32_e32 v35, v35
	v_add_f32_e32 v161, v161, v32
	v_bfi_b32 v35, v141, 0, v35
	v_add_u32_e32 v141, 0xfffffbb1, v66
	v_min_u32_e32 v142, 0x7f, v141
	v_lshl_add_u32 v142, v142, 2, s33
	ds_read_b32 v142, v142
	v_ashrrev_i32_e32 v141, 31, v141
	s_waitcnt lgkmcnt(14)
	v_add_f32_e32 v34, v37, v144
	v_exp_f32_e32 v34, v34
	v_add_f32_e32 v161, v161, v35
	v_bfi_b32 v34, v143, 0, v34
	v_add_u32_e32 v143, 0xfffffb61, v66
	v_min_u32_e32 v144, 0x7f, v143
	v_lshl_add_u32 v144, v144, 2, s33
	ds_read_b32 v144, v144
	v_ashrrev_i32_e32 v143, 31, v143
	s_waitcnt lgkmcnt(14)
	v_add_f32_e32 v37, v38, v146
	v_exp_f32_e32 v37, v37
	v_add_f32_e32 v161, v161, v34
	v_bfi_b32 v37, v145, 0, v37
	v_add_u32_e32 v145, 0xfffffb51, v66
	v_min_u32_e32 v146, 0x7f, v145
	v_lshl_add_u32 v146, v146, 2, s33
	ds_read_b32 v146, v146
	v_ashrrev_i32_e32 v145, 31, v145
	s_waitcnt lgkmcnt(14)
	v_add_f32_e32 v36, v39, v148
	v_exp_f32_e32 v36, v36
	v_add_f32_e32 v161, v161, v37
	v_bfi_b32 v36, v147, 0, v36
	v_add_u32_e32 v147, 0xfffffb41, v66
	v_min_u32_e32 v148, 0x7f, v147
	v_lshl_add_u32 v148, v148, 2, s33
	ds_read_b32 v148, v148
	v_ashrrev_i32_e32 v147, 31, v147
	s_waitcnt lgkmcnt(14)
	v_add_f32_e32 v39, v40, v150
	v_exp_f32_e32 v39, v39
	v_add_f32_e32 v161, v161, v36
	v_bfi_b32 v39, v149, 0, v39
	v_add_u32_e32 v149, 0xfffffb31, v66
	v_min_u32_e32 v150, 0x7f, v149
	v_lshl_add_u32 v150, v150, 2, s33
	ds_read_b32 v150, v150
	v_ashrrev_i32_e32 v149, 31, v149
	s_waitcnt lgkmcnt(14)
	v_add_f32_e32 v38, v41, v152
	v_exp_f32_e32 v38, v38
	v_add_f32_e32 v161, v161, v39
	v_bfi_b32 v38, v151, 0, v38
	v_add_u32_e32 v151, 0xfffffae1, v66
	v_min_u32_e32 v152, 0x7f, v151
	v_lshl_add_u32 v152, v152, 2, s33
	ds_read_b32 v152, v152
	v_ashrrev_i32_e32 v151, 31, v151
	s_waitcnt lgkmcnt(14)
	v_add_f32_e32 v41, v42, v154
	v_exp_f32_e32 v41, v41
	v_add_f32_e32 v161, v161, v38
	v_bfi_b32 v41, v153, 0, v41
	v_add_u32_e32 v153, 0xfffffad1, v66
	v_min_u32_e32 v154, 0x7f, v153
	v_lshl_add_u32 v154, v154, 2, s33
	ds_read_b32 v154, v154
	v_ashrrev_i32_e32 v153, 31, v153
	s_waitcnt lgkmcnt(14)
	v_add_f32_e32 v40, v43, v156
	v_exp_f32_e32 v40, v40
	v_add_f32_e32 v161, v161, v41
	v_bfi_b32 v40, v155, 0, v40
	v_add_u32_e32 v155, 0xfffffac1, v66
	v_min_u32_e32 v156, 0x7f, v155
	v_lshl_add_u32 v156, v156, 2, s33
	ds_read_b32 v156, v156
	v_ashrrev_i32_e32 v155, 31, v155
	s_waitcnt lgkmcnt(14)
	v_add_f32_e32 v67, v44, v158
	v_exp_f32_e32 v67, v67
	v_add_f32_e32 v161, v161, v40
	v_bfi_b32 v67, v157, 0, v67
	v_add_u32_e32 v157, 0xfffffab1, v66
	v_min_u32_e32 v158, 0x7f, v157
	v_lshl_add_u32 v158, v158, 2, s33
	ds_read_b32 v158, v158
	v_ashrrev_i32_e32 v157, 31, v157
	s_waitcnt lgkmcnt(14)
	v_add_f32_e32 v43, v45, v160
	v_exp_f32_e32 v43, v43
	v_add_f32_e32 v161, v161, v67
	v_bfi_b32 v43, v159, 0, v43
	v_add_u32_e32 v159, 0xfffffa61, v66
	v_min_u32_e32 v160, 0x7f, v159
	v_lshl_add_u32 v160, v160, 2, s33
	ds_read_b32 v160, v160
	v_ashrrev_i32_e32 v159, 31, v159
	s_waitcnt lgkmcnt(14)
	v_add_f32_e32 v69, v46, v132
	v_exp_f32_e32 v69, v69
	v_add_f32_e32 v161, v161, v43
	v_bfi_b32 v69, v131, 0, v69
	v_add_u32_e32 v131, 0xfffffa51, v66
	v_min_u32_e32 v132, 0x7f, v131
	v_lshl_add_u32 v132, v132, 2, s33
	ds_read_b32 v132, v132
	v_ashrrev_i32_e32 v131, 31, v131
	s_waitcnt lgkmcnt(14)
	v_add_f32_e32 v68, v47, v134
	v_exp_f32_e32 v68, v68
	v_add_f32_e32 v161, v161, v69
	v_bfi_b32 v68, v133, 0, v68
	v_add_u32_e32 v133, 0xfffffa41, v66
	v_min_u32_e32 v134, 0x7f, v133
	v_lshl_add_u32 v134, v134, 2, s33
	ds_read_b32 v134, v134
	v_ashrrev_i32_e32 v133, 31, v133
	s_waitcnt lgkmcnt(14)
	v_add_f32_e32 v44, v16, v136
	v_exp_f32_e32 v44, v44
	v_add_f32_e32 v161, v161, v68
	v_bfi_b32 v44, v135, 0, v44
	v_add_u32_e32 v135, 0xfffffa31, v66
	v_min_u32_e32 v136, 0x7f, v135
	v_lshl_add_u32 v136, v136, 2, s33
	ds_read_b32 v136, v136
	v_ashrrev_i32_e32 v135, 31, v135
	s_waitcnt lgkmcnt(14)
	v_add_f32_e32 v42, v17, v138
	v_exp_f32_e32 v42, v42
	v_add_f32_e32 v161, v161, v44
	v_bfi_b32 v42, v137, 0, v42
	v_add_u32_e32 v137, 0xfffff9e1, v66
	v_min_u32_e32 v138, 0x7f, v137
	v_lshl_add_u32 v138, v138, 2, s33
	ds_read_b32 v138, v138
	v_ashrrev_i32_e32 v137, 31, v137
	s_waitcnt lgkmcnt(14)
	v_add_f32_e32 v46, v18, v140
	v_exp_f32_e32 v46, v46
	v_add_f32_e32 v161, v161, v42
	v_bfi_b32 v46, v139, 0, v46
	v_add_u32_e32 v139, 0xfffff9d1, v66
	v_min_u32_e32 v140, 0x7f, v139
	v_lshl_add_u32 v140, v140, 2, s33
	ds_read_b32 v140, v140
	v_ashrrev_i32_e32 v139, 31, v139
	s_waitcnt lgkmcnt(14)
	v_add_f32_e32 v45, v19, v142
	v_exp_f32_e32 v45, v45
	v_add_f32_e32 v161, v161, v46
	v_bfi_b32 v45, v141, 0, v45
	v_add_u32_e32 v141, 0xfffff9c1, v66
	v_min_u32_e32 v142, 0x7f, v141
	v_lshl_add_u32 v142, v142, 2, s33
	ds_read_b32 v142, v142
	v_ashrrev_i32_e32 v141, 31, v141
	s_waitcnt lgkmcnt(14)
	v_add_f32_e32 v70, v20, v144
	v_exp_f32_e32 v70, v70
	v_add_f32_e32 v161, v161, v45
	v_bfi_b32 v70, v143, 0, v70
	v_add_u32_e32 v143, 0xfffff9b1, v66
	v_min_u32_e32 v144, 0x7f, v143
	v_lshl_add_u32 v144, v144, 2, s33
	ds_read_b32 v144, v144
	v_ashrrev_i32_e32 v143, 31, v143
	s_waitcnt lgkmcnt(14)
	v_add_f32_e32 v47, v21, v146
	v_exp_f32_e32 v47, v47
	v_add_f32_e32 v161, v161, v70
	v_bfi_b32 v47, v145, 0, v47
	v_add_u32_e32 v145, 0xfffff961, v66
	v_min_u32_e32 v146, 0x7f, v145
	v_lshl_add_u32 v146, v146, 2, s33
	ds_read_b32 v146, v146
	v_ashrrev_i32_e32 v145, 31, v145
	s_waitcnt lgkmcnt(14)
	v_add_f32_e32 v72, v22, v148
	v_exp_f32_e32 v72, v72
	v_add_f32_e32 v161, v161, v47
	v_bfi_b32 v72, v147, 0, v72
	v_add_u32_e32 v147, 0xfffff951, v66
	v_min_u32_e32 v148, 0x7f, v147
	v_lshl_add_u32 v148, v148, 2, s33
	ds_read_b32 v148, v148
	v_ashrrev_i32_e32 v147, 31, v147
	s_waitcnt lgkmcnt(14)
	v_add_f32_e32 v71, v23, v150
	v_exp_f32_e32 v71, v71
	v_add_f32_e32 v161, v161, v72
	v_bfi_b32 v71, v149, 0, v71
	v_add_u32_e32 v149, 0xfffff941, v66
	v_min_u32_e32 v150, 0x7f, v149
	v_lshl_add_u32 v150, v150, 2, s33
	ds_read_b32 v150, v150
	v_ashrrev_i32_e32 v149, 31, v149
	s_waitcnt lgkmcnt(14)
	v_add_f32_e32 v74, v24, v152
	v_exp_f32_e32 v74, v74
	v_add_f32_e32 v161, v161, v71
	v_bfi_b32 v74, v151, 0, v74
	v_add_u32_e32 v151, 0xfffff931, v66
	v_min_u32_e32 v152, 0x7f, v151
	v_lshl_add_u32 v152, v152, 2, s33
	ds_read_b32 v152, v152
	v_ashrrev_i32_e32 v151, 31, v151
	s_waitcnt lgkmcnt(14)
	v_add_f32_e32 v73, v25, v154
	v_exp_f32_e32 v73, v73
	v_add_f32_e32 v161, v161, v74
	v_bfi_b32 v73, v153, 0, v73
	v_add_u32_e32 v153, 0xfffff8e1, v66
	v_min_u32_e32 v154, 0x7f, v153
	v_lshl_add_u32 v154, v154, 2, s33
	ds_read_b32 v154, v154
	v_ashrrev_i32_e32 v153, 31, v153
	s_waitcnt lgkmcnt(14)
	v_add_f32_e32 v76, v26, v156
	v_exp_f32_e32 v76, v76
	v_add_f32_e32 v161, v161, v73
	v_bfi_b32 v76, v155, 0, v76
	v_add_u32_e32 v155, 0xfffff8d1, v66
	v_min_u32_e32 v156, 0x7f, v155
	v_lshl_add_u32 v156, v156, 2, s33
	ds_read_b32 v156, v156
	v_ashrrev_i32_e32 v155, 31, v155
	s_waitcnt lgkmcnt(14)
	v_add_f32_e32 v75, v27, v158
	v_exp_f32_e32 v75, v75
	v_add_f32_e32 v161, v161, v76
	v_bfi_b32 v75, v157, 0, v75
	v_add_u32_e32 v157, 0xfffff8c1, v66
	v_min_u32_e32 v158, 0x7f, v157
	v_lshl_add_u32 v158, v158, 2, s33
	ds_read_b32 v158, v158
	v_ashrrev_i32_e32 v157, 31, v157
	s_waitcnt lgkmcnt(14)
	v_add_f32_e32 v78, v28, v160
	v_exp_f32_e32 v78, v78
	v_add_f32_e32 v161, v161, v75
	v_bfi_b32 v78, v159, 0, v78
	v_add_u32_e32 v159, 0xfffff8b1, v66
	v_min_u32_e32 v160, 0x7f, v159
	v_lshl_add_u32 v160, v160, 2, s33
	ds_read_b32 v160, v160
	v_ashrrev_i32_e32 v159, 31, v159
	s_waitcnt lgkmcnt(14)
	v_add_f32_e32 v77, v29, v132
	v_exp_f32_e32 v77, v77
	v_add_f32_e32 v161, v161, v78
	v_bfi_b32 v77, v131, 0, v77
	v_add_u32_e32 v131, 0xfffff861, v66
	v_min_u32_e32 v132, 0x7f, v131
	v_lshl_add_u32 v132, v132, 2, s33
	ds_read_b32 v132, v132
	v_ashrrev_i32_e32 v131, 31, v131
	s_waitcnt lgkmcnt(14)
	v_add_f32_e32 v80, v30, v134
	v_exp_f32_e32 v80, v80
	v_add_f32_e32 v161, v161, v77
	v_bfi_b32 v80, v133, 0, v80
	v_add_u32_e32 v133, 0xfffff851, v66
	v_min_u32_e32 v134, 0x7f, v133
	v_lshl_add_u32 v134, v134, 2, s33
	ds_read_b32 v134, v134
	v_ashrrev_i32_e32 v133, 31, v133
	s_waitcnt lgkmcnt(14)
	v_add_f32_e32 v79, v31, v136
	v_exp_f32_e32 v79, v79
	v_add_f32_e32 v161, v161, v80
	v_bfi_b32 v79, v135, 0, v79
	v_add_u32_e32 v135, 0xfffff841, v66
	v_min_u32_e32 v136, 0x7f, v135
	v_lshl_add_u32 v136, v136, 2, s33
	ds_read_b32 v136, v136
	v_ashrrev_i32_e32 v135, 31, v135
	s_waitcnt lgkmcnt(14)
	v_add_f32_e32 v82, v0, v138
	v_exp_f32_e32 v82, v82
	v_add_f32_e32 v161, v161, v79
	v_bfi_b32 v82, v137, 0, v82
	v_add_u32_e32 v137, 0xfffff831, v66
	v_min_u32_e32 v138, 0x7f, v137
	v_lshl_add_u32 v138, v138, 2, s33
	ds_read_b32 v138, v138
	v_ashrrev_i32_e32 v137, 31, v137
	s_waitcnt lgkmcnt(14)
	v_add_f32_e32 v81, v1, v140
	v_exp_f32_e32 v81, v81
	v_add_f32_e32 v161, v161, v82
	v_bfi_b32 v81, v139, 0, v81
	s_waitcnt lgkmcnt(13)
	v_add_f32_e32 v84, v2, v142
	v_exp_f32_e32 v84, v84
	v_add_f32_e32 v161, v161, v81
	v_bfi_b32 v84, v141, 0, v84
	s_waitcnt lgkmcnt(12)
	v_add_f32_e32 v83, v3, v144
	v_exp_f32_e32 v83, v83
	v_add_f32_e32 v161, v161, v84
	v_bfi_b32 v83, v143, 0, v83
	s_waitcnt lgkmcnt(11)
	v_add_f32_e32 v86, v4, v146
	v_exp_f32_e32 v86, v86
	v_add_f32_e32 v161, v161, v83
	v_bfi_b32 v86, v145, 0, v86
	s_waitcnt lgkmcnt(10)
	v_add_f32_e32 v85, v5, v148
	v_exp_f32_e32 v85, v85
	v_add_f32_e32 v161, v161, v86
	v_bfi_b32 v85, v147, 0, v85
	s_waitcnt lgkmcnt(9)
	v_add_f32_e32 v88, v6, v150
	v_exp_f32_e32 v88, v88
	v_add_f32_e32 v161, v161, v85
	v_bfi_b32 v88, v149, 0, v88
	s_waitcnt lgkmcnt(8)
	v_add_f32_e32 v87, v7, v152
	v_exp_f32_e32 v87, v87
	v_add_f32_e32 v161, v161, v88
	v_bfi_b32 v87, v151, 0, v87
	s_waitcnt lgkmcnt(7)
	v_add_f32_e32 v90, v8, v154
	v_exp_f32_e32 v90, v90
	v_add_f32_e32 v161, v161, v87
	v_bfi_b32 v90, v153, 0, v90
	s_waitcnt lgkmcnt(6)
	v_add_f32_e32 v89, v9, v156
	v_exp_f32_e32 v89, v89
	v_add_f32_e32 v161, v161, v90
	v_bfi_b32 v89, v155, 0, v89
	s_waitcnt lgkmcnt(5)
	v_add_f32_e32 v92, v10, v158
	v_exp_f32_e32 v92, v92
	v_add_f32_e32 v161, v161, v89
	v_bfi_b32 v92, v157, 0, v92
	s_waitcnt lgkmcnt(4)
	v_add_f32_e32 v91, v11, v160
	v_exp_f32_e32 v91, v91
	v_add_f32_e32 v161, v161, v92
	v_bfi_b32 v91, v159, 0, v91
	s_waitcnt lgkmcnt(3)
	v_add_f32_e32 v94, v12, v132
	v_exp_f32_e32 v94, v94
	v_add_f32_e32 v161, v161, v91
	v_bfi_b32 v94, v131, 0, v94
	s_waitcnt lgkmcnt(2)
	v_add_f32_e32 v93, v13, v134
	v_exp_f32_e32 v93, v93
	v_add_f32_e32 v161, v161, v94
	v_bfi_b32 v93, v133, 0, v93
	s_waitcnt lgkmcnt(1)
	v_add_f32_e32 v130, v14, v136
	v_exp_f32_e32 v130, v130
	v_add_f32_e32 v161, v161, v93
	v_bfi_b32 v130, v135, 0, v130
	s_waitcnt lgkmcnt(0)
	v_add_f32_e32 v95, v15, v138
	v_exp_f32_e32 v95, v95
	v_add_f32_e32 v161, v161, v130
	v_bfi_b32 v95, v137, 0, v95
	v_add_f32_e32 v0, v161, v95
	v_readlane_b32 s0, v253, 1
	s_lshl_b32 s2, s0, 13
	ds_bpermute_b32 v1, v163, v0
	v_mul_f32_e32 v2, 0.5, v48
	ds_bpermute_b32 v2, v163, v2
	v_readlane_b32 s4, v251, 42
	v_readlane_b32 s5, v251, 43
	s_waitcnt lgkmcnt(1)
	v_add_f32_e32 v0, v0, v1
	v_div_scale_f32 v1, s[0:1], v0, v0, 1.0
	v_rcp_f32_e32 v3, v1
	v_div_scale_f32 v4, vcc, 1.0, v0, 1.0
	s_lshl_b32 s0, s2, 1
	v_fma_f32 v5, -v1, v3, 1.0
	v_fmac_f32_e32 v3, v5, v3
	v_mul_f32_e32 v5, v4, v3
	v_fma_f32 v6, -v1, v5, v4
	v_fmac_f32_e32 v5, v6, v3
	v_fma_f32 v1, -v1, v5, v4
	v_div_fmas_f32 v1, v1, v3, v5
	v_div_fixup_f32 v1, v1, v0, 1.0
	v_cmp_lt_f32_e32 vcc, 0, v0
	v_add_f32_e32 v0, v65, v64
	v_add_f32_e32 v3, v51, v50
	v_cndmask_b32_e32 v66, 0, v1, vcc
	v_fma_f32 v1, 0.5, v48, v49
	v_add_f32_e32 v0, v0, v1
	s_waitcnt lgkmcnt(0)
	v_cndmask_b32_e64 v1, v2, 0, s[4:5]
	v_add_f32_e32 v0, v0, v1
	v_mul_f32_e32 v1, 0.5, v52
	ds_bpermute_b32 v1, v163, v1
	v_fma_f32 v4, 0.5, v52, v53
	v_add_f32_e32 v3, v3, v4
	v_mul_f32_e32 v0, v66, v0
	v_fma_f32 v4, 0.5, v60, v61
	s_waitcnt lgkmcnt(0)
	v_cndmask_b32_e64 v2, v1, v2, s[4:5]
	v_add_f32_e32 v2, v3, v2
	v_mul_f32_e32 v3, 0.5, v56
	ds_bpermute_b32 v3, v163, v3
	v_mul_f32_e32 v2, v66, v2
	ds_write2_b32 v239, v0, v2 offset1:2
	v_add_f32_e32 v0, v55, v54
	v_fma_f32 v2, 0.5, v56, v57
	v_add_f32_e32 v0, v0, v2
	s_waitcnt lgkmcnt(1)
	v_cndmask_b32_e64 v1, v3, v1, s[4:5]
	v_add_f32_e32 v0, v0, v1
	v_mul_f32_e32 v1, 0.5, v60
	ds_bpermute_b32 v1, v163, v1
	v_add_f32_e32 v2, v59, v58
	v_add_f32_e32 v2, v2, v4
	v_mul_f32_e32 v0, v66, v0
	v_fma_f32 v4, 0.5, v36, v37
	s_waitcnt lgkmcnt(0)
	v_cndmask_b32_e64 v3, v1, v3, s[4:5]
	v_add_f32_e32 v2, v2, v3
	v_mul_f32_e32 v3, 0.5, v32
	ds_bpermute_b32 v3, v163, v3
	v_mul_f32_e32 v2, v66, v2
	ds_write2_b32 v239, v0, v2 offset0:4 offset1:6
	v_add_f32_e32 v0, v63, v62
	v_fma_f32 v2, 0.5, v32, v33
	v_add_f32_e32 v0, v0, v2
	s_waitcnt lgkmcnt(1)
	v_cndmask_b32_e64 v1, v3, v1, s[4:5]
	v_add_f32_e32 v0, v0, v1
	v_mul_f32_e32 v1, 0.5, v36
	ds_bpermute_b32 v1, v163, v1
	v_add_f32_e32 v2, v35, v34
	v_add_f32_e32 v2, v2, v4
	v_readlane_b32 s2, v252, 62
	v_mul_f32_e32 v0, v66, v0
	s_waitcnt lgkmcnt(0)
	v_cndmask_b32_e64 v3, v1, v3, s[4:5]
	v_add_f32_e32 v2, v2, v3
	v_mul_f32_e32 v3, 0.5, v40
	ds_bpermute_b32 v4, v163, v3
	v_mul_f32_e32 v2, v66, v2
	v_readlane_b32 s3, v252, 63
	s_add_u32 s0, s2, s0
	ds_write2_b32 v239, v0, v2 offset0:8 offset1:10
	v_add_f32_e32 v0, v39, v38
	v_fma_f32 v2, 0.5, v40, v41
	s_addc_u32 s1, s3, 0
	v_mov_b32_e32 v189, v97
	v_add_f32_e32 v5, v0, v2
	s_waitcnt lgkmcnt(1)
	v_cndmask_b32_e64 v6, v4, v1, s[4:5]
	v_lshl_add_u64 v[0:1], s[0:1], 0, v[188:189]
	s_mov_b64 s[0:1], 0x5200000
	v_lshl_add_u64 v[0:1], v[0:1], 0, s[0:1]
	v_mov_b32_e32 v191, v97
	v_lshl_add_u64 v[156:157], v[0:1], 0, v[190:191]
	v_mov_b32_e32 v193, v97
	v_lshl_add_u64 v[158:159], v[0:1], 0, v[192:193]
	v_and_b32_e32 v156, 31, v209
	v_and_b32_e32 v157, 7, v209
	v_lshlrev_b32_e32 v156, 8, v156
	v_lshl_add_u32 v156, v157, 5, v156
	v_lshrrev_b32_e32 v157, 5, v209
	v_lshl_add_u32 v156, v157, 4, v156
	v_add_u32_e32 v156, 0x24000, v156
	v_xor_b32_e32 v157, 32, v156
	v_xor_b32_e32 v158, 64, v156
	v_xor_b32_e32 v159, 0x60, v156
	ds_read_b128 v[0:3], v156
	ds_read_b128 v[132:135], v157
	ds_read_b128 v[16:19], v156 offset:8192
	ds_read_b128 v[136:139], v157 offset:8192
	ds_read_b128 v[140:143], v158
	ds_read_b128 v[144:147], v159
	ds_read_b128 v[148:151], v158 offset:8192
	ds_read_b128 v[152:155], v159 offset:8192
	v_add_f32_e32 v5, v5, v6
	v_mul_f32_e32 v6, 0.5, v68
	ds_bpermute_b32 v6, v163, v6
	v_add_f32_e32 v7, v67, v43
	v_fma_f32 v8, 0.5, v68, v69
	v_add_f32_e32 v7, v7, v8
	v_mul_f32_e32 v5, v66, v5
	s_waitcnt lgkmcnt(0)
	v_cndmask_b32_e64 v4, v6, v4, s[4:5]
	v_add_f32_e32 v4, v7, v4
	v_mul_f32_e32 v7, 0.5, v45
	ds_bpermute_b32 v7, v163, v7
	v_mul_f32_e32 v4, v66, v4
	ds_write2_b32 v239, v5, v4 offset0:12 offset1:14
	v_add_f32_e32 v4, v44, v42
	v_fma_f32 v5, 0.5, v45, v46
	v_add_f32_e32 v4, v4, v5
	s_waitcnt lgkmcnt(1)
	v_cndmask_b32_e64 v5, v7, v6, s[4:5]
	v_add_f32_e32 v4, v4, v5
	v_mul_f32_e32 v5, 0.5, v71
	ds_bpermute_b32 v5, v163, v5
	v_add_f32_e32 v6, v70, v47
	v_fma_f32 v8, 0.5, v71, v72
	v_add_f32_e32 v6, v6, v8
	v_mul_f32_e32 v4, v66, v4
	s_waitcnt lgkmcnt(0)
	v_cndmask_b32_e64 v7, v5, v7, s[4:5]
	v_add_f32_e32 v6, v6, v7
	v_mul_f32_e32 v7, 0.5, v75
	ds_bpermute_b32 v7, v163, v7
	v_mul_f32_e32 v6, v66, v6
	ds_write2_b32 v239, v4, v6 offset0:16 offset1:18
	v_add_f32_e32 v4, v74, v73
	v_fma_f32 v6, 0.5, v75, v76
	v_add_f32_e32 v4, v4, v6
	s_waitcnt lgkmcnt(1)
	v_cndmask_b32_e64 v5, v7, v5, s[4:5]
	v_add_f32_e32 v4, v4, v5
	v_mul_f32_e32 v5, 0.5, v79
	ds_bpermute_b32 v5, v163, v5
	v_add_f32_e32 v6, v78, v77
	v_fma_f32 v8, 0.5, v79, v80
	v_add_f32_e32 v6, v6, v8
	v_mul_f32_e32 v4, v66, v4
	s_waitcnt lgkmcnt(0)
	v_cndmask_b32_e64 v7, v5, v7, s[4:5]
	v_add_f32_e32 v6, v6, v7
	v_mul_f32_e32 v7, 0.5, v83
	ds_bpermute_b32 v7, v163, v7
	v_mul_f32_e32 v6, v66, v6
	ds_write2_b32 v239, v4, v6 offset0:20 offset1:22
	v_add_f32_e32 v4, v82, v81
	v_fma_f32 v6, 0.5, v83, v84
	v_add_f32_e32 v4, v4, v6
	s_waitcnt lgkmcnt(1)
	v_cndmask_b32_e64 v5, v7, v5, s[4:5]
	v_add_f32_e32 v4, v4, v5
	v_mul_f32_e32 v5, 0.5, v87
	ds_bpermute_b32 v5, v163, v5
	v_add_f32_e32 v6, v86, v85
	v_fma_f32 v8, 0.5, v87, v88
	v_add_f32_e32 v6, v6, v8
	v_mul_f32_e32 v4, v66, v4
	s_waitcnt lgkmcnt(0)
	v_cndmask_b32_e64 v7, v5, v7, s[4:5]
	v_add_f32_e32 v6, v6, v7
	v_mul_f32_e32 v7, 0.5, v91
	ds_bpermute_b32 v7, v163, v7
	v_mul_f32_e32 v6, v66, v6
	ds_write2_b32 v239, v4, v6 offset0:24 offset1:26
	v_add_f32_e32 v4, v90, v89
	v_fma_f32 v6, 0.5, v91, v92
	v_add_f32_e32 v4, v4, v6
	s_waitcnt lgkmcnt(1)
	v_cndmask_b32_e64 v5, v7, v5, s[4:5]
	v_add_f32_e32 v4, v4, v5
	v_mul_f32_e32 v5, 0.5, v95
	ds_bpermute_b32 v5, v163, v5
	v_add_f32_e32 v6, v94, v93
	v_fma_f32 v8, 0.5, v95, v130
	v_add_f32_e32 v6, v6, v8
	v_mul_f32_e32 v4, v66, v4
	s_waitcnt lgkmcnt(0)
	v_cndmask_b32_e64 v5, v5, v7, s[4:5]
	v_add_f32_e32 v5, v6, v5
	v_mul_f32_e32 v5, v66, v5
	ds_write2_b32 v239, v4, v5 offset0:28 offset1:30
	v_cvt_pk_bf16_f32 v20, v65, v64
	v_cvt_pk_bf16_f32 v21, v49, v48
	v_cvt_pk_bf16_f32 v22, v51, v50
	v_cvt_pk_bf16_f32 v23, v53, v52
	v_cvt_pk_bf16_f32 v48, v55, v54
	v_cvt_pk_bf16_f32 v49, v57, v56
	s_waitcnt vmcnt(0) lgkmcnt(0)
	v_mfma_f32_32x32x16_bf16 v[0:15], v[0:3], v[20:23], 0
	v_cvt_pk_bf16_f32 v50, v59, v58
	v_cvt_pk_bf16_f32 v51, v61, v60
	s_waitcnt vmcnt(10)
	v_mfma_f32_32x32x16_bf16 v[16:31], v[16:19], v[20:23], 0
	v_mfma_f32_32x32x16_bf16 v[0:15], v[132:135], v[48:51], v[0:15]
	s_waitcnt vmcnt(8)
	v_mfma_f32_32x32x16_bf16 v[16:31], v[136:139], v[48:51], v[16:31]
	v_cvt_pk_bf16_f32 v48, v63, v62
	v_cvt_pk_bf16_f32 v49, v33, v32
	v_cvt_pk_bf16_f32 v50, v35, v34
	v_cvt_pk_bf16_f32 v51, v37, v36
	v_cvt_pk_bf16_f32 v32, v39, v38
	v_cvt_pk_bf16_f32 v33, v41, v40
	v_cvt_pk_bf16_f32 v34, v67, v43
	s_waitcnt vmcnt(6)
	v_mfma_f32_32x32x16_bf16 v[0:15], v[140:143], v[48:51], v[0:15]
	v_cvt_pk_bf16_f32 v35, v69, v68
	s_waitcnt vmcnt(2)
	v_mfma_f32_32x32x16_bf16 v[16:31], v[148:151], v[48:51], v[16:31]
	v_mfma_f32_32x32x16_bf16 v[0:15], v[144:147], v[32:35], v[0:15]
	s_waitcnt vmcnt(0)
	v_mfma_f32_32x32x16_bf16 v[16:31], v[152:155], v[32:35], v[16:31]
	v_xor_b32_e32 v157, 0x80, v156
	v_xor_b32_e32 v158, 0xa0, v156
	v_xor_b32_e32 v159, 0xc0, v156
	v_xor_b32_e32 v156, 0xe0, v156
	ds_read_b128 v[32:35], v157
	ds_read_b128 v[36:39], v157 offset:8192
	ds_read_b128 v[48:51], v158
	ds_read_b128 v[52:55], v158 offset:8192
	ds_read_b128 v[56:59], v159
	ds_read_b128 v[60:63], v159 offset:8192
	ds_read_b128 v[132:135], v156
	ds_read_b128 v[136:139], v156 offset:8192
	v_cvt_pk_bf16_f32 v40, v44, v42
	v_cvt_pk_bf16_f32 v41, v46, v45
	v_cvt_pk_bf16_f32 v42, v70, v47
	v_cvt_pk_bf16_f32 v43, v72, v71
	v_readlane_b32 s0, v251, 44
	v_readlane_b32 s1, v251, 45
	s_waitcnt lgkmcnt(7)
	v_mfma_f32_32x32x16_bf16 v[0:15], v[32:35], v[40:43], v[0:15]
	v_cvt_pk_bf16_f32 v32, v74, v73
	v_cvt_pk_bf16_f32 v33, v76, v75
	v_cvt_pk_bf16_f32 v34, v78, v77
	v_cvt_pk_bf16_f32 v35, v80, v79
	s_mov_b64 s[14:15], -1
	s_mov_b64 s[12:13], -1
	s_waitcnt lgkmcnt(6)
	v_mfma_f32_32x32x16_bf16 v[16:31], v[36:39], v[40:43], v[16:31]
	s_waitcnt lgkmcnt(5)
	v_mfma_f32_32x32x16_bf16 v[0:15], v[48:51], v[32:35], v[0:15]
	s_waitcnt lgkmcnt(4)
	v_mfma_f32_32x32x16_bf16 v[16:31], v[52:55], v[32:35], v[16:31]
	v_cvt_pk_bf16_f32 v32, v82, v81
	v_cvt_pk_bf16_f32 v33, v84, v83
	v_cvt_pk_bf16_f32 v34, v86, v85
	v_cvt_pk_bf16_f32 v35, v88, v87
	s_waitcnt lgkmcnt(3)
	s_nop 0
	v_mfma_f32_32x32x16_bf16 v[0:15], v[56:59], v[32:35], v[0:15]
	s_waitcnt lgkmcnt(2)
	v_mfma_f32_32x32x16_bf16 v[16:31], v[60:63], v[32:35], v[16:31]
	v_cvt_pk_bf16_f32 v32, v90, v89
	v_cvt_pk_bf16_f32 v33, v92, v91
	v_cvt_pk_bf16_f32 v34, v94, v93
	v_cvt_pk_bf16_f32 v35, v130, v95
	s_waitcnt lgkmcnt(1)
	s_nop 0
	v_mfma_f32_32x32x16_bf16 v[0:15], v[132:135], v[32:35], v[0:15]
	s_waitcnt lgkmcnt(0)
	v_mfma_f32_32x32x16_bf16 v[16:31], v[136:139], v[32:35], v[16:31]
	v_mul_f32_e32 v32, v162, v66
	s_nop 8
	v_mul_f32_e32 v0, v32, v0
	v_mul_f32_e32 v1, v32, v1
	ds_write2st64_b32 v173, v0, v1 offset1:1
	v_mul_f32_e32 v16, v32, v16
	v_mul_f32_e32 v0, v32, v17
	ds_write2st64_b32 v173, v16, v0 offset0:16 offset1:17
	v_mul_f32_e32 v0, v32, v2
	v_mul_f32_e32 v2, v32, v3
	v_mul_f32_e32 v1, v32, v18
	ds_write2st64_b32 v173, v0, v2 offset0:2 offset1:3
	v_mul_f32_e32 v0, v32, v19
	ds_write2st64_b32 v173, v1, v0 offset0:18 offset1:19
	v_mul_f32_e32 v0, v32, v4
	v_mul_f32_e32 v2, v32, v5
	v_mul_f32_e32 v1, v32, v20
	ds_write2st64_b32 v173, v0, v2 offset0:4 offset1:5
	v_mul_f32_e32 v0, v32, v21
	ds_write2st64_b32 v173, v1, v0 offset0:20 offset1:21
	v_mul_f32_e32 v0, v32, v6
	v_mul_f32_e32 v2, v32, v7
	v_mul_f32_e32 v1, v32, v22
	ds_write2st64_b32 v173, v0, v2 offset0:6 offset1:7
	v_mul_f32_e32 v0, v32, v23
	ds_write2st64_b32 v173, v1, v0 offset0:22 offset1:23
	v_mul_f32_e32 v0, v32, v8
	v_mul_f32_e32 v2, v32, v9
	v_mul_f32_e32 v1, v32, v24
	ds_write2st64_b32 v173, v0, v2 offset0:8 offset1:9
	v_mul_f32_e32 v0, v32, v25
	ds_write2st64_b32 v173, v1, v0 offset0:24 offset1:25
	v_mul_f32_e32 v0, v32, v10
	v_mul_f32_e32 v2, v32, v11
	v_mul_f32_e32 v1, v32, v26
	ds_write2st64_b32 v173, v0, v2 offset0:10 offset1:11
	v_mul_f32_e32 v0, v32, v27
	ds_write2st64_b32 v173, v1, v0 offset0:26 offset1:27
	v_mul_f32_e32 v0, v32, v12
	v_mul_f32_e32 v2, v32, v13
	v_mul_f32_e32 v1, v32, v28
	ds_write2st64_b32 v173, v0, v2 offset0:12 offset1:13
	v_mul_f32_e32 v0, v32, v29
	ds_write2st64_b32 v173, v1, v0 offset0:28 offset1:29
	v_mul_f32_e32 v0, v32, v14
	v_mul_f32_e32 v2, v32, v15
	v_mul_f32_e32 v1, v32, v30
	ds_write2st64_b32 v173, v0, v2 offset0:14 offset1:15
	v_mul_f32_e32 v0, v32, v31
	ds_write2st64_b32 v173, v1, v0 offset0:30 offset1:31
	s_waitcnt lgkmcnt(0)
	s_barrier
	s_add_i32 s51, s50, -2
	s_lshl_b32 s16, 1, s50
	s_lshr_b32 s17, s16, 1
	s_or_b32 s16, s16, s17
	s_or_b32 s16, s16, 1
	s_bcnt1_i32_b32 s17, s16
	s_sub_i32 s17, 8, s17
	s_max_i32 s18, s51, 0
	v_lshl_add_u32 v134, v177, 2, v240
	ds_read_b128 v[80:83], v134
	ds_read_b128 v[84:87], v134 offset:9216
	ds_read_b128 v[88:91], v134 offset:18432
	ds_read_b128 v[92:95], v134 offset:27648
	ds_read_b128 v[32:35], v240
	ds_read_b128 v[36:39], v240 offset:9216
	ds_read_b128 v[40:43], v240 offset:18432
	ds_read_b128 v[44:47], v240 offset:27648
	ds_read_b128 v[48:51], v240 offset:16
	ds_read_b128 v[52:55], v240 offset:9232
	ds_read_b128 v[56:59], v240 offset:18448
	ds_read_b128 v[60:63], v240 offset:27664
	s_waitcnt lgkmcnt(8)
	v_pk_add_f32 v[80:81], v[80:81], v[84:85]
	v_pk_add_f32 v[82:83], v[82:83], v[86:87]
	v_pk_add_f32 v[88:89], v[88:89], v[92:93]
	v_pk_add_f32 v[90:91], v[90:91], v[94:95]
	v_pk_add_f32 v[80:81], v[80:81], v[88:89]
	v_pk_add_f32 v[82:83], v[82:83], v[90:91]
	ds_read_b128 v[64:67], v240 offset:32
	ds_read_b128 v[68:71], v240 offset:9248
	ds_read_b128 v[72:75], v240 offset:18464
	ds_read_b128 v[76:79], v240 offset:27680
	v_add_u32_e32 v140, -1, v177
	v_add_u32_e32 v141, 0, v177
	v_add_u32_e32 v142, 1, v177
	v_add_u32_e32 v143, 2, v177
	v_cmp_gt_u32_e64 s[20:21], s18, v140
	v_cmp_gt_u32_e64 s[22:23], s18, v141
	v_cmp_gt_u32_e64 s[24:25], s18, v142
	v_cmp_gt_u32_e64 s[26:27], s18, v143
	v_mov_b32_e32 v136, 0
	v_mov_b32_e32 v137, 0
	v_mov_b32_e32 v138, 0
	v_mov_b32_e32 v139, 0
	v_cndmask_b32_e64 v80, -1, v80, s[20:21]
	v_cndmask_b32_e64 v81, -1, v81, s[22:23]
	v_cndmask_b32_e64 v82, -1, v82, s[24:25]
	v_cndmask_b32_e64 v83, -1, v83, s[26:27]
	v_add_u32_e32 v84, -1, v80
	v_add_u32_e32 v85, -1, v81
	v_add_u32_e32 v86, -1, v82
	v_add_u32_e32 v87, -1, v83
	s_waitcnt lgkmcnt(8)
	v_pk_add_f32 v[32:33], v[32:33], v[36:37]
	v_pk_add_f32 v[34:35], v[34:35], v[38:39]
	v_pk_add_f32 v[40:41], v[40:41], v[44:45]
	v_pk_add_f32 v[42:43], v[42:43], v[46:47]
	v_pk_add_f32 v[0:1], v[32:33], v[40:41]
	v_pk_add_f32 v[2:3], v[34:35], v[42:43]
	ds_read_b128 v[32:35], v240 offset:48
	ds_read_b128 v[36:39], v240 offset:9264
	ds_read_b128 v[40:43], v240 offset:18480
	ds_read_b128 v[44:47], v240 offset:27696
	v_cmp_le_u32_e64 s[30:31], 4, v177
	s_cmp_gt_i32 s18, 0
	s_cselect_b64 s[28:29], -1, 0
	v_cndmask_b32_e64 v1, -1, v1, s[28:29]
	s_cmp_gt_i32 s18, 1
	s_cselect_b64 s[28:29], -1, 0
	v_cndmask_b32_e64 v2, -1, v2, s[28:29]
	s_cmp_gt_i32 s18, 2
	s_cselect_b64 s[28:29], -1, 0
	v_cndmask_b32_e64 v3, -1, v3, s[28:29]
	v_cndmask_b32_e64 v92, v80, v84, s[30:31]
	v_cndmask_b32_e64 v93, v81, v85, s[30:31]
	v_cndmask_b32_e64 v94, v82, v86, s[30:31]
	v_cndmask_b32_e64 v95, v83, v87, s[30:31]
	v_cmp_gt_i32_e64 s[38:39], v1, v92
	v_cmp_gt_i32_e64 s[40:41], v1, v93
	v_cmp_gt_i32_e64 s[42:43], v1, v86
	v_cmp_gt_i32_e64 s[44:45], v1, v87
	v_addc_co_u32_e64 v136, s[36:37], 0, v136, s[38:39]
	v_addc_co_u32_e64 v137, s[36:37], 0, v137, s[40:41]
	v_addc_co_u32_e64 v138, s[36:37], 0, v138, s[42:43]
	v_addc_co_u32_e64 v139, s[36:37], 0, v139, s[44:45]
	v_cmp_gt_i32_e64 s[38:39], v2, v92
	v_cmp_gt_i32_e64 s[40:41], v2, v93
	v_cmp_gt_i32_e64 s[42:43], v2, v94
	v_cmp_gt_i32_e64 s[44:45], v2, v87
	v_addc_co_u32_e64 v136, s[36:37], 0, v136, s[38:39]
	v_addc_co_u32_e64 v137, s[36:37], 0, v137, s[40:41]
	v_addc_co_u32_e64 v138, s[36:37], 0, v138, s[42:43]
	v_addc_co_u32_e64 v139, s[36:37], 0, v139, s[44:45]
	v_cmp_gt_i32_e64 s[38:39], v3, v92
	v_cmp_gt_i32_e64 s[40:41], v3, v93
	v_cmp_gt_i32_e64 s[42:43], v3, v94
	v_cmp_gt_i32_e64 s[44:45], v3, v95
	v_addc_co_u32_e64 v136, s[36:37], 0, v136, s[38:39]
	v_addc_co_u32_e64 v137, s[36:37], 0, v137, s[40:41]
	v_addc_co_u32_e64 v138, s[36:37], 0, v138, s[42:43]
	v_addc_co_u32_e64 v139, s[36:37], 0, v139, s[44:45]
	s_waitcnt lgkmcnt(8)
	v_pk_add_f32 v[48:49], v[48:49], v[52:53]
	v_pk_add_f32 v[50:51], v[50:51], v[54:55]
	v_pk_add_f32 v[56:57], v[56:57], v[60:61]
	v_pk_add_f32 v[58:59], v[58:59], v[62:63]
	v_pk_add_f32 v[4:5], v[48:49], v[56:57]
	v_pk_add_f32 v[6:7], v[50:51], v[58:59]
	ds_read_b128 v[48:51], v240 offset:64
	ds_read_b128 v[52:55], v240 offset:9280
	ds_read_b128 v[56:59], v240 offset:18496
	ds_read_b128 v[60:63], v240 offset:27712
	v_cmp_le_u32_e64 s[30:31], 8, v177
	s_cmp_gt_i32 s18, 3
	s_cselect_b64 s[28:29], -1, 0
	v_cndmask_b32_e64 v4, -1, v4, s[28:29]
	s_cmp_gt_i32 s18, 4
	s_cselect_b64 s[28:29], -1, 0
	v_cndmask_b32_e64 v5, -1, v5, s[28:29]
	s_cmp_gt_i32 s18, 5
	s_cselect_b64 s[28:29], -1, 0
	v_cndmask_b32_e64 v6, -1, v6, s[28:29]
	s_cmp_gt_i32 s18, 6
	s_cselect_b64 s[28:29], -1, 0
	v_cndmask_b32_e64 v7, -1, v7, s[28:29]
	v_cndmask_b32_e64 v88, v80, v84, s[30:31]
	v_cndmask_b32_e64 v89, v81, v85, s[30:31]
	v_cndmask_b32_e64 v90, v82, v86, s[30:31]
	v_cndmask_b32_e64 v91, v83, v87, s[30:31]
	v_cmp_gt_i32_e64 s[38:39], v4, v88
	v_cmp_gt_i32_e64 s[40:41], v4, v93
	v_cmp_gt_i32_e64 s[42:43], v4, v94
	v_cmp_gt_i32_e64 s[44:45], v4, v95
	v_addc_co_u32_e64 v136, s[36:37], 0, v136, s[38:39]
	v_addc_co_u32_e64 v137, s[36:37], 0, v137, s[40:41]
	v_addc_co_u32_e64 v138, s[36:37], 0, v138, s[42:43]
	v_addc_co_u32_e64 v139, s[36:37], 0, v139, s[44:45]
	v_cmp_gt_i32_e64 s[38:39], v5, v88
	v_cmp_gt_i32_e64 s[40:41], v5, v89
	v_cmp_gt_i32_e64 s[42:43], v5, v94
	v_cmp_gt_i32_e64 s[44:45], v5, v95
	v_addc_co_u32_e64 v136, s[36:37], 0, v136, s[38:39]
	v_addc_co_u32_e64 v137, s[36:37], 0, v137, s[40:41]
	v_addc_co_u32_e64 v138, s[36:37], 0, v138, s[42:43]
	v_addc_co_u32_e64 v139, s[36:37], 0, v139, s[44:45]
	v_cmp_gt_i32_e64 s[38:39], v6, v88
	v_cmp_gt_i32_e64 s[40:41], v6, v89
	v_cmp_gt_i32_e64 s[42:43], v6, v90
	v_cmp_gt_i32_e64 s[44:45], v6, v95
	v_addc_co_u32_e64 v136, s[36:37], 0, v136, s[38:39]
	v_addc_co_u32_e64 v137, s[36:37], 0, v137, s[40:41]
	v_addc_co_u32_e64 v138, s[36:37], 0, v138, s[42:43]
	v_addc_co_u32_e64 v139, s[36:37], 0, v139, s[44:45]
	v_cmp_gt_i32_e64 s[38:39], v7, v88
	v_cmp_gt_i32_e64 s[40:41], v7, v89
	v_cmp_gt_i32_e64 s[42:43], v7, v90
	v_cmp_gt_i32_e64 s[44:45], v7, v91
	v_addc_co_u32_e64 v136, s[36:37], 0, v136, s[38:39]
	v_addc_co_u32_e64 v137, s[36:37], 0, v137, s[40:41]
	v_addc_co_u32_e64 v138, s[36:37], 0, v138, s[42:43]
	v_addc_co_u32_e64 v139, s[36:37], 0, v139, s[44:45]
	s_waitcnt lgkmcnt(8)
	v_pk_add_f32 v[64:65], v[64:65], v[68:69]
	v_pk_add_f32 v[66:67], v[66:67], v[70:71]
	v_pk_add_f32 v[72:73], v[72:73], v[76:77]
	v_pk_add_f32 v[74:75], v[74:75], v[78:79]
	v_pk_add_f32 v[8:9], v[64:65], v[72:73]
	v_pk_add_f32 v[10:11], v[66:67], v[74:75]
	ds_read_b128 v[64:67], v240 offset:80
	ds_read_b128 v[68:71], v240 offset:9296
	ds_read_b128 v[72:75], v240 offset:18512
	ds_read_b128 v[76:79], v240 offset:27728
	v_cmp_le_u32_e64 s[30:31], 12, v177
	s_cmp_gt_i32 s18, 7
	s_cselect_b64 s[28:29], -1, 0
	v_cndmask_b32_e64 v8, -1, v8, s[28:29]
	s_cmp_gt_i32 s18, 8
	s_cselect_b64 s[28:29], -1, 0
	v_cndmask_b32_e64 v9, -1, v9, s[28:29]
	s_cmp_gt_i32 s18, 9
	s_cselect_b64 s[28:29], -1, 0
	v_cndmask_b32_e64 v10, -1, v10, s[28:29]
	s_cmp_gt_i32 s18, 10
	s_cselect_b64 s[28:29], -1, 0
	v_cndmask_b32_e64 v11, -1, v11, s[28:29]
	v_cndmask_b32_e64 v92, v80, v84, s[30:31]
	v_cndmask_b32_e64 v93, v81, v85, s[30:31]
	v_cndmask_b32_e64 v94, v82, v86, s[30:31]
	v_cndmask_b32_e64 v95, v83, v87, s[30:31]
	v_cmp_gt_i32_e64 s[38:39], v8, v92
	v_cmp_gt_i32_e64 s[40:41], v8, v89
	v_cmp_gt_i32_e64 s[42:43], v8, v90
	v_cmp_gt_i32_e64 s[44:45], v8, v91
	v_addc_co_u32_e64 v136, s[36:37], 0, v136, s[38:39]
	v_addc_co_u32_e64 v137, s[36:37], 0, v137, s[40:41]
	v_addc_co_u32_e64 v138, s[36:37], 0, v138, s[42:43]
	v_addc_co_u32_e64 v139, s[36:37], 0, v139, s[44:45]
	v_cmp_gt_i32_e64 s[38:39], v9, v92
	v_cmp_gt_i32_e64 s[40:41], v9, v93
	v_cmp_gt_i32_e64 s[42:43], v9, v90
	v_cmp_gt_i32_e64 s[44:45], v9, v91
	v_addc_co_u32_e64 v136, s[36:37], 0, v136, s[38:39]
	v_addc_co_u32_e64 v137, s[36:37], 0, v137, s[40:41]
	v_addc_co_u32_e64 v138, s[36:37], 0, v138, s[42:43]
	v_addc_co_u32_e64 v139, s[36:37], 0, v139, s[44:45]
	v_cmp_gt_i32_e64 s[38:39], v10, v92
	v_cmp_gt_i32_e64 s[40:41], v10, v93
	v_cmp_gt_i32_e64 s[42:43], v10, v94
	v_cmp_gt_i32_e64 s[44:45], v10, v91
	v_addc_co_u32_e64 v136, s[36:37], 0, v136, s[38:39]
	v_addc_co_u32_e64 v137, s[36:37], 0, v137, s[40:41]
	v_addc_co_u32_e64 v138, s[36:37], 0, v138, s[42:43]
	v_addc_co_u32_e64 v139, s[36:37], 0, v139, s[44:45]
	v_cmp_gt_i32_e64 s[38:39], v11, v92
	v_cmp_gt_i32_e64 s[40:41], v11, v93
	v_cmp_gt_i32_e64 s[42:43], v11, v94
	v_cmp_gt_i32_e64 s[44:45], v11, v95
	v_addc_co_u32_e64 v136, s[36:37], 0, v136, s[38:39]
	v_addc_co_u32_e64 v137, s[36:37], 0, v137, s[40:41]
	v_addc_co_u32_e64 v138, s[36:37], 0, v138, s[42:43]
	v_addc_co_u32_e64 v139, s[36:37], 0, v139, s[44:45]
	s_waitcnt lgkmcnt(8)
	v_pk_add_f32 v[32:33], v[32:33], v[36:37]
	v_pk_add_f32 v[34:35], v[34:35], v[38:39]
	v_pk_add_f32 v[40:41], v[40:41], v[44:45]
	v_pk_add_f32 v[42:43], v[42:43], v[46:47]
	v_pk_add_f32 v[12:13], v[32:33], v[40:41]
	v_pk_add_f32 v[14:15], v[34:35], v[42:43]
	ds_read_b128 v[32:35], v240 offset:96
	ds_read_b128 v[36:39], v240 offset:9312
	ds_read_b128 v[40:43], v240 offset:18528
	ds_read_b128 v[44:47], v240 offset:27744
	v_cmp_le_u32_e64 s[30:31], 16, v177
	s_cmp_gt_i32 s18, 11
	s_cselect_b64 s[28:29], -1, 0
	v_cndmask_b32_e64 v12, -1, v12, s[28:29]
	s_cmp_gt_i32 s18, 12
	s_cselect_b64 s[28:29], -1, 0
	v_cndmask_b32_e64 v13, -1, v13, s[28:29]
	s_cmp_gt_i32 s18, 13
	s_cselect_b64 s[28:29], -1, 0
	v_cndmask_b32_e64 v14, -1, v14, s[28:29]
	s_cmp_gt_i32 s18, 14
	s_cselect_b64 s[28:29], -1, 0
	v_cndmask_b32_e64 v15, -1, v15, s[28:29]
	v_cndmask_b32_e64 v88, v80, v84, s[30:31]
	v_cndmask_b32_e64 v89, v81, v85, s[30:31]
	v_cndmask_b32_e64 v90, v82, v86, s[30:31]
	v_cndmask_b32_e64 v91, v83, v87, s[30:31]
	v_cmp_gt_i32_e64 s[38:39], v12, v88
	v_cmp_gt_i32_e64 s[40:41], v12, v93
	v_cmp_gt_i32_e64 s[42:43], v12, v94
	v_cmp_gt_i32_e64 s[44:45], v12, v95
	v_addc_co_u32_e64 v136, s[36:37], 0, v136, s[38:39]
	v_addc_co_u32_e64 v137, s[36:37], 0, v137, s[40:41]
	v_addc_co_u32_e64 v138, s[36:37], 0, v138, s[42:43]
	v_addc_co_u32_e64 v139, s[36:37], 0, v139, s[44:45]
	v_cmp_gt_i32_e64 s[38:39], v13, v88
	v_cmp_gt_i32_e64 s[40:41], v13, v89
	v_cmp_gt_i32_e64 s[42:43], v13, v94
	v_cmp_gt_i32_e64 s[44:45], v13, v95
	v_addc_co_u32_e64 v136, s[36:37], 0, v136, s[38:39]
	v_addc_co_u32_e64 v137, s[36:37], 0, v137, s[40:41]
	v_addc_co_u32_e64 v138, s[36:37], 0, v138, s[42:43]
	v_addc_co_u32_e64 v139, s[36:37], 0, v139, s[44:45]
	v_cmp_gt_i32_e64 s[38:39], v14, v88
	v_cmp_gt_i32_e64 s[40:41], v14, v89
	v_cmp_gt_i32_e64 s[42:43], v14, v90
	v_cmp_gt_i32_e64 s[44:45], v14, v95
	v_addc_co_u32_e64 v136, s[36:37], 0, v136, s[38:39]
	v_addc_co_u32_e64 v137, s[36:37], 0, v137, s[40:41]
	v_addc_co_u32_e64 v138, s[36:37], 0, v138, s[42:43]
	v_addc_co_u32_e64 v139, s[36:37], 0, v139, s[44:45]
	v_cmp_gt_i32_e64 s[38:39], v15, v88
	v_cmp_gt_i32_e64 s[40:41], v15, v89
	v_cmp_gt_i32_e64 s[42:43], v15, v90
	v_cmp_gt_i32_e64 s[44:45], v15, v91
	v_addc_co_u32_e64 v136, s[36:37], 0, v136, s[38:39]
	v_addc_co_u32_e64 v137, s[36:37], 0, v137, s[40:41]
	v_addc_co_u32_e64 v138, s[36:37], 0, v138, s[42:43]
	v_addc_co_u32_e64 v139, s[36:37], 0, v139, s[44:45]
	s_waitcnt lgkmcnt(8)
	v_pk_add_f32 v[48:49], v[48:49], v[52:53]
	v_pk_add_f32 v[50:51], v[50:51], v[54:55]
	v_pk_add_f32 v[56:57], v[56:57], v[60:61]
	v_pk_add_f32 v[58:59], v[58:59], v[62:63]
	v_pk_add_f32 v[16:17], v[48:49], v[56:57]
	v_pk_add_f32 v[18:19], v[50:51], v[58:59]
	ds_read_b128 v[48:51], v240 offset:112
	ds_read_b128 v[52:55], v240 offset:9328
	ds_read_b128 v[56:59], v240 offset:18544
	ds_read_b128 v[60:63], v240 offset:27760
	v_cmp_le_u32_e64 s[30:31], 20, v177
	s_cmp_gt_i32 s18, 15
	s_cselect_b64 s[28:29], -1, 0
	v_cndmask_b32_e64 v16, -1, v16, s[28:29]
	s_cmp_gt_i32 s18, 16
	s_cselect_b64 s[28:29], -1, 0
	v_cndmask_b32_e64 v17, -1, v17, s[28:29]
	s_cmp_gt_i32 s18, 17
	s_cselect_b64 s[28:29], -1, 0
	v_cndmask_b32_e64 v18, -1, v18, s[28:29]
	s_cmp_gt_i32 s18, 18
	s_cselect_b64 s[28:29], -1, 0
	v_cndmask_b32_e64 v19, -1, v19, s[28:29]
	v_cndmask_b32_e64 v92, v80, v84, s[30:31]
	v_cndmask_b32_e64 v93, v81, v85, s[30:31]
	v_cndmask_b32_e64 v94, v82, v86, s[30:31]
	v_cndmask_b32_e64 v95, v83, v87, s[30:31]
	v_cmp_gt_i32_e64 s[38:39], v16, v92
	v_cmp_gt_i32_e64 s[40:41], v16, v89
	v_cmp_gt_i32_e64 s[42:43], v16, v90
	v_cmp_gt_i32_e64 s[44:45], v16, v91
	v_addc_co_u32_e64 v136, s[36:37], 0, v136, s[38:39]
	v_addc_co_u32_e64 v137, s[36:37], 0, v137, s[40:41]
	v_addc_co_u32_e64 v138, s[36:37], 0, v138, s[42:43]
	v_addc_co_u32_e64 v139, s[36:37], 0, v139, s[44:45]
	v_cmp_gt_i32_e64 s[38:39], v17, v92
	v_cmp_gt_i32_e64 s[40:41], v17, v93
	v_cmp_gt_i32_e64 s[42:43], v17, v90
	v_cmp_gt_i32_e64 s[44:45], v17, v91
	v_addc_co_u32_e64 v136, s[36:37], 0, v136, s[38:39]
	v_addc_co_u32_e64 v137, s[36:37], 0, v137, s[40:41]
	v_addc_co_u32_e64 v138, s[36:37], 0, v138, s[42:43]
	v_addc_co_u32_e64 v139, s[36:37], 0, v139, s[44:45]
	v_cmp_gt_i32_e64 s[38:39], v18, v92
	v_cmp_gt_i32_e64 s[40:41], v18, v93
	v_cmp_gt_i32_e64 s[42:43], v18, v94
	v_cmp_gt_i32_e64 s[44:45], v18, v91
	v_addc_co_u32_e64 v136, s[36:37], 0, v136, s[38:39]
	v_addc_co_u32_e64 v137, s[36:37], 0, v137, s[40:41]
	v_addc_co_u32_e64 v138, s[36:37], 0, v138, s[42:43]
	v_addc_co_u32_e64 v139, s[36:37], 0, v139, s[44:45]
	v_cmp_gt_i32_e64 s[38:39], v19, v92
	v_cmp_gt_i32_e64 s[40:41], v19, v93
	v_cmp_gt_i32_e64 s[42:43], v19, v94
	v_cmp_gt_i32_e64 s[44:45], v19, v95
	v_addc_co_u32_e64 v136, s[36:37], 0, v136, s[38:39]
	v_addc_co_u32_e64 v137, s[36:37], 0, v137, s[40:41]
	v_addc_co_u32_e64 v138, s[36:37], 0, v138, s[42:43]
	v_addc_co_u32_e64 v139, s[36:37], 0, v139, s[44:45]
	s_waitcnt lgkmcnt(8)
	v_pk_add_f32 v[64:65], v[64:65], v[68:69]
	v_pk_add_f32 v[66:67], v[66:67], v[70:71]
	v_pk_add_f32 v[72:73], v[72:73], v[76:77]
	v_pk_add_f32 v[74:75], v[74:75], v[78:79]
	v_pk_add_f32 v[20:21], v[64:65], v[72:73]
	v_pk_add_f32 v[22:23], v[66:67], v[74:75]
	v_cmp_le_u32_e64 s[30:31], 24, v177
	s_cmp_gt_i32 s18, 19
	s_cselect_b64 s[28:29], -1, 0
	v_cndmask_b32_e64 v20, -1, v20, s[28:29]
	s_cmp_gt_i32 s18, 20
	s_cselect_b64 s[28:29], -1, 0
	v_cndmask_b32_e64 v21, -1, v21, s[28:29]
	s_cmp_gt_i32 s18, 21
	s_cselect_b64 s[28:29], -1, 0
	v_cndmask_b32_e64 v22, -1, v22, s[28:29]
	s_cmp_gt_i32 s18, 22
	s_cselect_b64 s[28:29], -1, 0
	v_cndmask_b32_e64 v23, -1, v23, s[28:29]
	v_cndmask_b32_e64 v88, v80, v84, s[30:31]
	v_cndmask_b32_e64 v89, v81, v85, s[30:31]
	v_cndmask_b32_e64 v90, v82, v86, s[30:31]
	v_cndmask_b32_e64 v91, v83, v87, s[30:31]
	v_cmp_gt_i32_e64 s[38:39], v20, v88
	v_cmp_gt_i32_e64 s[40:41], v20, v93
	v_cmp_gt_i32_e64 s[42:43], v20, v94
	v_cmp_gt_i32_e64 s[44:45], v20, v95
	v_addc_co_u32_e64 v136, s[36:37], 0, v136, s[38:39]
	v_addc_co_u32_e64 v137, s[36:37], 0, v137, s[40:41]
	v_addc_co_u32_e64 v138, s[36:37], 0, v138, s[42:43]
	v_addc_co_u32_e64 v139, s[36:37], 0, v139, s[44:45]
	v_cmp_gt_i32_e64 s[38:39], v21, v88
	v_cmp_gt_i32_e64 s[40:41], v21, v89
	v_cmp_gt_i32_e64 s[42:43], v21, v94
	v_cmp_gt_i32_e64 s[44:45], v21, v95
	v_addc_co_u32_e64 v136, s[36:37], 0, v136, s[38:39]
	v_addc_co_u32_e64 v137, s[36:37], 0, v137, s[40:41]
	v_addc_co_u32_e64 v138, s[36:37], 0, v138, s[42:43]
	v_addc_co_u32_e64 v139, s[36:37], 0, v139, s[44:45]
	v_cmp_gt_i32_e64 s[38:39], v22, v88
	v_cmp_gt_i32_e64 s[40:41], v22, v89
	v_cmp_gt_i32_e64 s[42:43], v22, v90
	v_cmp_gt_i32_e64 s[44:45], v22, v95
	v_addc_co_u32_e64 v136, s[36:37], 0, v136, s[38:39]
	v_addc_co_u32_e64 v137, s[36:37], 0, v137, s[40:41]
	v_addc_co_u32_e64 v138, s[36:37], 0, v138, s[42:43]
	v_addc_co_u32_e64 v139, s[36:37], 0, v139, s[44:45]
	v_cmp_gt_i32_e64 s[38:39], v23, v88
	v_cmp_gt_i32_e64 s[40:41], v23, v89
	v_cmp_gt_i32_e64 s[42:43], v23, v90
	v_cmp_gt_i32_e64 s[44:45], v23, v91
	v_addc_co_u32_e64 v136, s[36:37], 0, v136, s[38:39]
	v_addc_co_u32_e64 v137, s[36:37], 0, v137, s[40:41]
	v_addc_co_u32_e64 v138, s[36:37], 0, v138, s[42:43]
	v_addc_co_u32_e64 v139, s[36:37], 0, v139, s[44:45]
	s_waitcnt lgkmcnt(4)
	v_pk_add_f32 v[32:33], v[32:33], v[36:37]
	v_pk_add_f32 v[34:35], v[34:35], v[38:39]
	v_pk_add_f32 v[40:41], v[40:41], v[44:45]
	v_pk_add_f32 v[42:43], v[42:43], v[46:47]
	v_pk_add_f32 v[24:25], v[32:33], v[40:41]
	v_pk_add_f32 v[26:27], v[34:35], v[42:43]
	v_cmp_le_u32_e64 s[30:31], 28, v177
	s_cmp_gt_i32 s18, 23
	s_cselect_b64 s[28:29], -1, 0
	v_cndmask_b32_e64 v24, -1, v24, s[28:29]
	s_cmp_gt_i32 s18, 24
	s_cselect_b64 s[28:29], -1, 0
	v_cndmask_b32_e64 v25, -1, v25, s[28:29]
	s_cmp_gt_i32 s18, 25
	s_cselect_b64 s[28:29], -1, 0
	v_cndmask_b32_e64 v26, -1, v26, s[28:29]
	s_cmp_gt_i32 s18, 26
	s_cselect_b64 s[28:29], -1, 0
	v_cndmask_b32_e64 v27, -1, v27, s[28:29]
	v_cndmask_b32_e64 v92, v80, v84, s[30:31]
	v_cndmask_b32_e64 v93, v81, v85, s[30:31]
	v_cndmask_b32_e64 v94, v82, v86, s[30:31]
	v_cndmask_b32_e64 v95, v83, v87, s[30:31]
	v_cmp_gt_i32_e64 s[38:39], v24, v92
	v_cmp_gt_i32_e64 s[40:41], v24, v89
	v_cmp_gt_i32_e64 s[42:43], v24, v90
	v_cmp_gt_i32_e64 s[44:45], v24, v91
	v_addc_co_u32_e64 v136, s[36:37], 0, v136, s[38:39]
	v_addc_co_u32_e64 v137, s[36:37], 0, v137, s[40:41]
	v_addc_co_u32_e64 v138, s[36:37], 0, v138, s[42:43]
	v_addc_co_u32_e64 v139, s[36:37], 0, v139, s[44:45]
	v_cmp_gt_i32_e64 s[38:39], v25, v92
	v_cmp_gt_i32_e64 s[40:41], v25, v93
	v_cmp_gt_i32_e64 s[42:43], v25, v90
	v_cmp_gt_i32_e64 s[44:45], v25, v91
	v_addc_co_u32_e64 v136, s[36:37], 0, v136, s[38:39]
	v_addc_co_u32_e64 v137, s[36:37], 0, v137, s[40:41]
	v_addc_co_u32_e64 v138, s[36:37], 0, v138, s[42:43]
	v_addc_co_u32_e64 v139, s[36:37], 0, v139, s[44:45]
	v_cmp_gt_i32_e64 s[38:39], v26, v92
	v_cmp_gt_i32_e64 s[40:41], v26, v93
	v_cmp_gt_i32_e64 s[42:43], v26, v94
	v_cmp_gt_i32_e64 s[44:45], v26, v91
	v_addc_co_u32_e64 v136, s[36:37], 0, v136, s[38:39]
	v_addc_co_u32_e64 v137, s[36:37], 0, v137, s[40:41]
	v_addc_co_u32_e64 v138, s[36:37], 0, v138, s[42:43]
	v_addc_co_u32_e64 v139, s[36:37], 0, v139, s[44:45]
	v_cmp_gt_i32_e64 s[38:39], v27, v92
	v_cmp_gt_i32_e64 s[40:41], v27, v93
	v_cmp_gt_i32_e64 s[42:43], v27, v94
	v_cmp_gt_i32_e64 s[44:45], v27, v95
	v_addc_co_u32_e64 v136, s[36:37], 0, v136, s[38:39]
	v_addc_co_u32_e64 v137, s[36:37], 0, v137, s[40:41]
	v_addc_co_u32_e64 v138, s[36:37], 0, v138, s[42:43]
	v_addc_co_u32_e64 v139, s[36:37], 0, v139, s[44:45]
	s_waitcnt lgkmcnt(0)
	v_pk_add_f32 v[48:49], v[48:49], v[52:53]
	v_pk_add_f32 v[50:51], v[50:51], v[54:55]
	v_pk_add_f32 v[56:57], v[56:57], v[60:61]
	v_pk_add_f32 v[58:59], v[58:59], v[62:63]
	v_pk_add_f32 v[28:29], v[48:49], v[56:57]
	v_pk_add_f32 v[30:31], v[50:51], v[58:59]
	s_cmp_gt_i32 s18, 27
	s_cselect_b64 s[28:29], -1, 0
	v_cndmask_b32_e64 v28, -1, v28, s[28:29]
	s_cmp_gt_i32 s18, 28
	s_cselect_b64 s[28:29], -1, 0
	v_cndmask_b32_e64 v29, -1, v29, s[28:29]
	v_cmp_gt_i32_e64 s[38:39], v28, v80
	v_cmp_gt_i32_e64 s[40:41], v28, v93
	v_cmp_gt_i32_e64 s[42:43], v28, v94
	v_cmp_gt_i32_e64 s[44:45], v28, v95
	v_addc_co_u32_e64 v136, s[36:37], 0, v136, s[38:39]
	v_addc_co_u32_e64 v137, s[36:37], 0, v137, s[40:41]
	v_addc_co_u32_e64 v138, s[36:37], 0, v138, s[42:43]
	v_addc_co_u32_e64 v139, s[36:37], 0, v139, s[44:45]
	v_cmp_gt_i32_e64 s[38:39], v29, v80
	v_cmp_gt_i32_e64 s[40:41], v29, v81
	v_cmp_gt_i32_e64 s[42:43], v29, v94
	v_cmp_gt_i32_e64 s[44:45], v29, v95
	v_addc_co_u32_e64 v136, s[36:37], 0, v136, s[38:39]
	v_addc_co_u32_e64 v137, s[36:37], 0, v137, s[40:41]
	v_addc_co_u32_e64 v138, s[36:37], 0, v138, s[42:43]
	v_addc_co_u32_e64 v139, s[36:37], 0, v139, s[44:45]
	v_cmp_gt_i32_e64 s[38:39], s17, v136
	v_cmp_gt_i32_e64 s[40:41], s17, v137
	v_cmp_gt_i32_e64 s[42:43], s17, v138
	v_cmp_gt_i32_e64 s[44:45], s17, v139
	s_and_b64 s[38:39], s[38:39], s[20:21]
	s_and_b64 s[40:41], s[40:41], s[22:23]
	s_and_b64 s[42:43], s[42:43], s[24:25]
	s_and_b64 s[44:45], s[44:45], s[26:27]
	v_cndmask_b32_e64 v140, 0, v231, s[38:39]
	v_cndmask_b32_e64 v141, 0, v232, s[40:41]
	v_cndmask_b32_e64 v142, 0, v234, s[42:43]
	v_cndmask_b32_e64 v143, 0, v236, s[44:45]
	v_or3_b32 v140, v140, v141, v142
	v_or_b32_e32 v140, v140, v143
	s_nop 1
	v_or_b32_dpp v141, v140, v140 quad_perm:[1,0,3,2] row_mask:0xf bank_mask:0xf
	s_nop 1
	v_or_b32_dpp v140, v141, v141 quad_perm:[2,3,0,1] row_mask:0xf bank_mask:0xf
	s_nop 1
	v_or_b32_dpp v141, v140, v140 row_half_mirror row_mask:0xf bank_mask:0xf
	v_cmp_eq_u32_e32 vcc, 0, v177
	v_or_b32_e32 v141, s16, v141
	s_and_saveexec_b64 s[0:1], vcc
	s_cbranch_execz .LBB0_398
	ds_write_b32 v179, v141

	.amdhsa_kernel _Z8yoco_fwd4Args
		.amdhsa_group_segment_fixed_size 16384
		.amdhsa_private_segment_fixed_size 0
		.amdhsa_kernarg_size 568
		.amdhsa_user_sgpr_count 2
		.amdhsa_user_sgpr_dispatch_ptr 0
		.amdhsa_user_sgpr_queue_ptr 0
		.amdhsa_user_sgpr_kernarg_segment_ptr 1
		.amdhsa_user_sgpr_dispatch_id 0
		.amdhsa_user_sgpr_kernarg_preload_length 0
		.amdhsa_user_sgpr_kernarg_preload_offset 0
		.amdhsa_user_sgpr_private_segment_size 0
		.amdhsa_uses_dynamic_stack 0
		.amdhsa_enable_private_segment 0
		.amdhsa_system_sgpr_workgroup_id_x 1
		.amdhsa_system_sgpr_workgroup_id_y 0
		.amdhsa_system_sgpr_workgroup_id_z 0
		.amdhsa_system_sgpr_workgroup_info 0
		.amdhsa_system_vgpr_workitem_id 2
		.amdhsa_next_free_vgpr 256
		.amdhsa_next_free_sgpr 102
		.amdhsa_accum_offset 256
		.amdhsa_reserve_vcc 1
		.amdhsa_float_round_mode_32 0
		.amdhsa_float_round_mode_16_64 0
		.amdhsa_float_denorm_mode_32 3
		.amdhsa_float_denorm_mode_16_64 3
		.amdhsa_dx10_clamp 1
		.amdhsa_ieee_mode 1
		.amdhsa_fp16_overflow 0
		.amdhsa_tg_split 0
		.amdhsa_exception_fp_ieee_invalid_op 0
		.amdhsa_exception_fp_denorm_src 0
		.amdhsa_exception_fp_ieee_div_zero 0
		.amdhsa_exception_fp_ieee_overflow 0
		.amdhsa_exception_fp_ieee_underflow 0
		.amdhsa_exception_fp_ieee_inexact 0
		.amdhsa_exception_int_div_zero 0
	.end_amdhsa_kernel

amdhsa.kernels:
  - .agpr_count:     0
    .args:
      - .offset:         0
        .size:           312
        .value_kind:     by_value
      - .offset:         312
        .size:           4
        .value_kind:     hidden_block_count_x
      - .offset:         316
        .size:           4
        .value_kind:     hidden_block_count_y
      - .offset:         320
        .size:           4
        .value_kind:     hidden_block_count_z
      - .offset:         324
        .size:           2
        .value_kind:     hidden_group_size_x
      - .offset:         326
        .size:           2
        .value_kind:     hidden_group_size_y
      - .offset:         328
        .size:           2
        .value_kind:     hidden_group_size_z
      - .offset:         330
        .size:           2
        .value_kind:     hidden_remainder_x
      - .offset:         332
        .size:           2
        .value_kind:     hidden_remainder_y
      - .offset:         334
        .size:           2
        .value_kind:     hidden_remainder_z
      - .offset:         352
        .size:           8
        .value_kind:     hidden_global_offset_x
      - .offset:         360
        .size:           8
        .value_kind:     hidden_global_offset_y
      - .offset:         368
        .size:           8
        .value_kind:     hidden_global_offset_z
      - .offset:         376
        .size:           2
        .value_kind:     hidden_grid_dims
      - .offset:         400
        .size:           8
        .value_kind:     hidden_multigrid_sync_arg
      - .offset:         432
        .size:           4
        .value_kind:     hidden_dynamic_lds_size
    .group_segment_fixed_size: 16384
    .kernarg_segment_align: 8
    .kernarg_segment_size: 568
    .language:       OpenCL C
    .language_version:
      - 2
      - 0
    .max_flat_workgroup_size: 512
    .name:           _Z8yoco_fwd4Args
    .private_segment_fixed_size: 0
    .sgpr_count:     108
    .sgpr_spill_count: 444
    .symbol:         _Z8yoco_fwd4Args.kd
    .uniform_work_group_size: 1
    .uses_dynamic_stack: false
    .vgpr_count:     256
    .vgpr_spill_count: 0
    .wavefront_size: 64
